# v24
# baseline (speedup 1.0000x reference)
; DI float fxc(const i64* p) { return (float)(*p) * FXC_INV; }
; DI void epi_rows(const Params& p, int L, int ekind, const float* T, int rbase, int bcol) {
;     ...
;     case E_SWI_A: case E_SWI_B: {
;       const bool a = ekind == E_SWI_A;
;       const i64* st = a ? (L > 0 ? ST_(L - 1, 2) : nullptr) : ST_(L, 1);
;       const int co = a ? CS_W13A : CS_W13B;
;       u16* act = (u16*)(R + R_ACT);
;       const int c = lane * 2;
;       float csg0 = 0, csg1 = 0, csu0 = 0, csu1 = 0, bwg0 = 0, bwg1 = 0, bwu0 = 0, bwu1 = 0;
;       float mu_l = 0.f, rstd_l = 1.f;
;       if (st) { const i64* q = cs + co + bcol + c; const i64* r = bw + co + bcol + c;
;         csg0 = fxc(q); csg1 = fxc(q + 1); csu0 = fxc(q + 128); csu1 = fxc(q + 129); bwg0 = fxc(r); bwg1 = fxc(r + 1); bwu0 = fxc(r + 128); bwu1 = fxc(r + 129);
;         RowStat rs = row_stat(st, myrow); mu_l = rs.mu; rstd_l = rs.rstd; }
; DI void epi_dispatch(const Params& p, int L, int ekind, f32x4 (&acc)[2][2][4][2], int brow, int bcol, int, int, int, int) {
;   float* T = (float*)smem;
;   int tid_ = threadIdx.x; asm volatile("" : "+v"(tid_));
;   const int wid_ = tid_ >> 6, lane_ = tid_ & 63, wr = wid_ >> 2, wc = wid_ & 3, fr = lane_ & 15, fq = lane_ >> 4;
;   float* tw = T + (wr * 64 + fq * 4) * TSTR + wc * 32 + fr;
;   #pragma unroll
;   for (int ai = 0; ai < 2; ++ai) {
;     __syncthreads();
;     #pragma unroll
;     for (int bj = 0; bj < 2; ++bj)
;       #pragma unroll
;       for (int m = 0; m < 4; ++m)
;         #pragma unroll
;         for (int n = 0; n < 2; ++n)
;           #pragma unroll
;           for (int j = 0; j < 4; ++j) tw[(m * 16 + j) * TSTR + bj * 128 + n * 16] = acc[ai][bj][m][n][j];
;     __syncthreads();
;     epi_rows(p, L, ekind, T, brow + ai * 128, bcol);
.LBB0_342:
	s_or_b64 exec, exec, s[12:13]
	v_mov_b32_e32 v0, v178
	s_movk_i32 s5, 0x410
	v_lshrrev_b32_e32 v131, 2, v0
	v_and_b32_e32 v131, 0xfffffcc, v131
	v_and_b32_e32 v130, 15, v0
	v_mul_lo_u32 v131, v131, s5
	v_lshlrev_b32_e32 v0, 1, v0
	v_add_u32_e32 v131, 0, v131
	v_and_b32_e32 v0, 0x180, v0
	v_lshlrev_b32_e32 v130, 2, v130
	v_add3_u32 v130, v131, v0, v130
	s_waitcnt vmcnt(0)
	s_barrier
	ds_write2_b32 v130, v114, v126 offset1:16
	v_add_u32_e32 v114, 0x400, v130
	ds_write2_b32 v114, v115, v127 offset0:4 offset1:20
	v_add_u32_e32 v115, 0x800, v130
	ds_write2_b32 v115, v116, v128 offset0:8 offset1:24
	v_add_u32_e32 v116, 0xc00, v130
	ds_write2_b32 v116, v117, v129 offset0:12 offset1:28
	v_add_u32_e32 v117, 0x4000, v130
	ds_write2_b32 v117, v82, v94 offset0:64 offset1:80
	v_add_u32_e32 v82, 0x4400, v130
	ds_write2_b32 v82, v83, v95 offset0:68 offset1:84
	v_add_u32_e32 v83, 0x4800, v130
	ds_write2_b32 v83, v84, v96 offset0:72 offset1:88
	v_add_u32_e32 v84, 0x4c00, v130
	ds_write2_b32 v84, v85, v97 offset0:76 offset1:92
	v_add_u32_e32 v85, 0x8400, v130
	ds_write2_b32 v85, v75, v79 offset0:132 offset1:148
	v_add_u32_e32 v79, 0x8800, v130
	ds_write2_b32 v79, v76, v80 offset0:136 offset1:152
	v_add_u32_e32 v80, 0x8c00, v130
	v_add_u32_e32 v96, 0x8000, v130
	ds_write2_b32 v80, v77, v81 offset0:140 offset1:156
	v_add_u32_e32 v97, 0xc000, v130
	v_add_u32_e32 v81, 0xc400, v130
	v_add_u32_e32 v94, 0xc800, v130
	v_add_u32_e32 v95, 0xcc00, v130
	ds_write2_b32 v96, v74, v78 offset0:128 offset1:144
	ds_write2_b32 v97, v66, v70 offset0:192 offset1:208
	ds_write2_b32 v81, v67, v71 offset0:196 offset1:212
	ds_write2_b32 v94, v68, v72 offset0:200 offset1:216
	ds_write2_b32 v95, v69, v73 offset0:204 offset1:220
	ds_write2_b32 v130, v98, v118 offset0:128 offset1:144
	ds_write2_b32 v114, v99, v119 offset0:132 offset1:148
	ds_write2_b32 v115, v100, v120 offset0:136 offset1:152
	ds_write2_b32 v116, v101, v121 offset0:140 offset1:156
	ds_write2_b32 v117, v102, v122 offset0:192 offset1:208
	ds_write2_b32 v82, v103, v123 offset0:196 offset1:212
	ds_write2_b32 v83, v104, v124 offset0:200 offset1:216
	ds_write2_b32 v84, v105, v125 offset0:204 offset1:220
	ds_write2_b32 v85, v90, v110 offset1:16
	ds_write2_b32 v79, v91, v111 offset0:4 offset1:20
	ds_write2_b32 v80, v92, v112 offset0:8 offset1:24
	v_add_u32_e32 v90, 0x9000, v130
	ds_write2_b32 v90, v93, v113 offset0:12 offset1:28
	ds_write2_b32 v81, v86, v106 offset0:64 offset1:80
	ds_write2_b32 v94, v87, v107 offset0:68 offset1:84
	ds_write2_b32 v95, v88, v108 offset0:72 offset1:88
	v_add_u32_e32 v86, 0xd000, v130
	s_mov_b64 s[12:13], s[70:71]
	v_mov_b32_e32 v87, v178
	ds_write2_b32 v86, v89, v109 offset0:76 offset1:92
	s_waitcnt lgkmcnt(0)
	s_barrier
	v_readlane_b32 s24, v254, 5
	v_readfirstlane_b32 s5, v87
	s_ashr_i32 s9, s5, 2
	v_lshlrev_b32_e32 v0, 1, v87
	v_readlane_b32 s25, v254, 6
	s_and_b32 s5, s9, -16
	v_and_b32_e32 v78, 0x7e, v0
	s_and_b64 vcc, exec, s[24:25]
	s_cbranch_vccz .LBB0_344
; DI float fxc(const i64* p) { return (float)(*p) * FXC_INV; }
; DI RowStat row_stat(const i64* st, int row) {
;   float s = (float)st[2 * (size_t)row] * FXS_INV, q = (float)st[2 * (size_t)row + 1] * FXS_INV;
;   float mu = s * (1.f / 1024.f);
;   float var = fmaxf(q * (1.f / 1024.f) - mu * mu, 0.f);
;   RowStat r; r.mu = mu; r.rstd = rsqrtf(var + 1e-5f); return r;
; DI void epi_rows(const Params& p, int L, int ekind, const float* T, int rbase, int bcol) {
;     ...
;       if (st) { const i64* q = cs + co + bcol + c; const i64* r = bw + co + bcol + c;
;         csg0 = fxc(q); csg1 = fxc(q + 1); csu0 = fxc(q + 128); csu1 = fxc(q + 129); bwg0 = fxc(r); bwg1 = fxc(r + 1); bwu0 = fxc(r + 128); bwu1 = fxc(r + 129);
;         RowStat rs = row_stat(st, myrow); mu_l = rs.mu; rstd_l = rs.rstd; }
	s_add_i32 s10, s5, s10
	v_and_or_b32 v66, v87, 15, s10
	v_readlane_b32 s10, v255, 12
	v_readlane_b32 s11, v255, 13
	s_lshl_b64 s[10:11], s[10:11], 3
	s_add_u32 s24, s12, s10
	s_addc_u32 s25, s13, s11
	s_lshl_b64 s[10:11], s[6:7], 3
	s_add_u32 s10, s24, s10
	s_addc_u32 s11, s25, s11
	v_lshlrev_b32_e32 v0, 3, v78
	v_lshl_add_u64 v[74:75], s[10:11], 0, v[0:1]
	s_mov_b64 s[10:11], 0x38e000
	v_lshl_add_u64 v[76:77], v[74:75], 0, s[10:11]
	s_mov_b64 s[10:11], 0x3c9000
	v_lshl_add_u64 v[68:69], v[74:75], 0, s[10:11]
	s_mov_b32 s10, 0x38e000
	v_add_co_u32_e32 v70, vcc, s10, v74
	flat_load_dwordx4 v[98:101], v[76:77] offset:1024
	s_nop 0
	v_addc_co_u32_e32 v71, vcc, 0, v75, vcc
	flat_load_dwordx4 v[70:73], v[70:71]
	s_mov_b32 s24, 0x2f800000
	s_mov_b32 s10, 0x3c9000
	v_add_co_u32_e32 v74, vcc, s10, v74
	s_mov_b32 s10, 0x104000
	s_nop 0
	v_addc_co_u32_e32 v75, vcc, 0, v75, vcc
	flat_load_dwordx4 v[188:191], v[74:75]
	flat_load_dwordx4 v[196:199], v[68:69] offset:1024
	v_mov_b32_e32 v208, v66
	v_ashrrev_i32_e32 v209, 31, v208
	v_lshl_add_u64 v[208:209], v[208:209], 4, s[12:13]
	v_add_co_u32_e32 v208, vcc, s10, v208
	s_nop 1
	v_addc_co_u32_e32 v209, vcc, 0, v209, vcc
	flat_load_dwordx4 v[204:207], v[208:209]
	s_waitcnt vmcnt(0) lgkmcnt(0)
	v_xor_b32_e32 v0, v72, v73
	v_ashrrev_i32_e32 v0, 31, v0
	v_ffbh_i32_e32 v67, v73
	v_add_u32_e32 v0, 32, v0
	v_add_u32_e32 v67, -1, v67
	v_min_u32_e32 v0, v67, v0
	v_lshlrev_b64 v[72:73], v0, v[72:73]
	v_min_u32_e32 v67, 1, v72
	v_or_b32_e32 v67, v73, v67
	v_cvt_f32_i32_e32 v67, v67
	v_sub_u32_e32 v0, 32, v0
	v_ldexp_f32 v73, v67, v0
	v_xor_b32_e32 v0, v70, v71
	v_ashrrev_i32_e32 v0, 31, v0
	v_ffbh_i32_e32 v67, v71
	v_add_u32_e32 v0, 32, v0
	v_add_u32_e32 v67, -1, v67
	v_min_u32_e32 v0, v67, v0
	v_lshlrev_b64 v[70:71], v0, v[70:71]
	v_min_u32_e32 v67, 1, v70
	v_or_b32_e32 v67, v71, v67
	v_cvt_f32_i32_e32 v67, v67
	v_sub_u32_e32 v0, 32, v0
	v_ldexp_f32 v72, v67, v0
	v_xor_b32_e32 v0, v100, v101
	v_ashrrev_i32_e32 v0, 31, v0
	v_ffbh_i32_e32 v67, v101
	v_add_u32_e32 v0, 32, v0
	v_add_u32_e32 v67, -1, v67
	v_min_u32_e32 v0, v67, v0
	v_pk_mul_f32 v[70:71], v[72:73], s[24:25] op_sel_hi:[1,0]
	v_lshlrev_b64 v[72:73], v0, v[100:101]
	v_min_u32_e32 v67, 1, v72
	v_or_b32_e32 v67, v73, v67
	v_cvt_f32_i32_e32 v67, v67
	v_sub_u32_e32 v0, 32, v0
	v_ldexp_f32 v73, v67, v0
	v_xor_b32_e32 v0, v98, v99
	v_ashrrev_i32_e32 v0, 31, v0
	v_ffbh_i32_e32 v67, v99
	v_add_u32_e32 v0, 32, v0
	v_add_u32_e32 v67, -1, v67
	v_min_u32_e32 v0, v67, v0
	v_lshlrev_b64 v[76:77], v0, v[98:99]
	v_min_u32_e32 v67, 1, v76
	v_or_b32_e32 v67, v77, v67
	v_mov_b64_e32 v[74:75], v[188:189]
	v_mov_b64_e32 v[76:77], v[190:191]
	v_cvt_f32_i32_e32 v67, v67
	v_mov_b64_e32 v[98:99], v[196:197]
	v_mov_b64_e32 v[100:101], v[198:199]
	v_sub_u32_e32 v0, 32, v0
	v_ldexp_f32 v72, v67, v0
	v_pk_mul_f32 v[72:73], v[72:73], s[24:25] op_sel_hi:[1,0]
	s_waitcnt vmcnt(0) lgkmcnt(0)
	v_xor_b32_e32 v0, v76, v77
	v_ashrrev_i32_e32 v0, 31, v0
	v_ffbh_i32_e32 v67, v77
	v_add_u32_e32 v0, 32, v0
	v_add_u32_e32 v67, -1, v67
	v_min_u32_e32 v0, v67, v0
	v_lshlrev_b64 v[76:77], v0, v[76:77]
	v_min_u32_e32 v67, 1, v76
	v_or_b32_e32 v67, v77, v67
	v_cvt_f32_i32_e32 v67, v67
	v_sub_u32_e32 v0, 32, v0
	v_ldexp_f32 v77, v67, v0
	v_xor_b32_e32 v0, v74, v75
	v_ashrrev_i32_e32 v0, 31, v0
	v_ffbh_i32_e32 v67, v75
	v_add_u32_e32 v0, 32, v0
	v_add_u32_e32 v67, -1, v67
	v_min_u32_e32 v0, v67, v0
	v_lshlrev_b64 v[74:75], v0, v[74:75]
	v_min_u32_e32 v67, 1, v74
	v_or_b32_e32 v67, v75, v67
	v_cvt_f32_i32_e32 v67, v67
	v_sub_u32_e32 v0, 32, v0
	v_ldexp_f32 v76, v67, v0
	v_xor_b32_e32 v0, v100, v101
	v_ashrrev_i32_e32 v0, 31, v0
	v_ffbh_i32_e32 v67, v101
	v_add_u32_e32 v0, 32, v0
	v_add_u32_e32 v67, -1, v67
	v_min_u32_e32 v0, v67, v0
	v_lshlrev_b64 v[68:69], v0, v[100:101]
	v_min_u32_e32 v67, 1, v68
	v_or_b32_e32 v67, v69, v67
	v_cvt_f32_i32_e32 v67, v67
	v_sub_u32_e32 v0, 32, v0
	v_pk_mul_f32 v[74:75], v[76:77], s[24:25] op_sel_hi:[1,0]
	v_ldexp_f32 v69, v67, v0
	v_xor_b32_e32 v0, v98, v99
	v_ashrrev_i32_e32 v0, 31, v0
	v_ffbh_i32_e32 v67, v99
	v_add_u32_e32 v0, 32, v0
	v_add_u32_e32 v67, -1, v67
	v_min_u32_e32 v0, v67, v0
	v_lshlrev_b64 v[76:77], v0, v[98:99]
	v_min_u32_e32 v67, 1, v76
	v_or_b32_e32 v67, v77, v67
	v_cvt_f32_i32_e32 v67, v67
	v_sub_u32_e32 v0, 32, v0
	v_ldexp_f32 v68, v67, v0
	v_ashrrev_i32_e32 v67, 31, v66
	v_lshl_add_u64 v[66:67], v[66:67], 4, s[12:13]
	v_add_co_u32_e32 v66, vcc, s10, v66
	v_pk_mul_f32 v[76:77], v[68:69], s[24:25] op_sel_hi:[1,0]
	s_nop 0
	v_addc_co_u32_e32 v67, vcc, 0, v67, vcc
	v_mov_b64_e32 v[66:67], v[204:205]
	v_mov_b64_e32 v[68:69], v[206:207]
	s_mov_b32 s10, 0x3a800000
	s_waitcnt vmcnt(0) lgkmcnt(0)
	v_xor_b32_e32 v0, v66, v67
	v_ashrrev_i32_e32 v0, 31, v0
	v_ffbh_i32_e32 v88, v67
	v_add_u32_e32 v0, 32, v0
	v_add_u32_e32 v88, -1, v88
	v_min_u32_e32 v0, v88, v0
	v_lshlrev_b64 v[66:67], v0, v[66:67]
	v_min_u32_e32 v66, 1, v66
	v_or_b32_e32 v66, v67, v66
	v_cvt_f32_i32_e32 v66, v66
	v_sub_u32_e32 v0, 32, v0
	v_ffbh_i32_e32 v67, v69
	v_add_u32_e32 v67, -1, v67
	v_ldexp_f32 v0, v66, v0
	v_xor_b32_e32 v66, v68, v69
	v_ashrrev_i32_e32 v66, 31, v66
	v_add_u32_e32 v66, 32, v66
	v_min_u32_e32 v88, v67, v66
	v_lshlrev_b64 v[66:67], v88, v[68:69]
	v_min_u32_e32 v66, 1, v66
	v_or_b32_e32 v66, v67, v66
	v_cvt_f32_i32_e32 v66, v66
	v_mul_f32_e32 v0, 0x33800000, v0
	v_sub_u32_e32 v67, 32, v88
	v_mul_f32_e32 v68, 0x3a800000, v0
	v_ldexp_f32 v66, v66, v67
	v_mul_f32_e32 v66, 0x33800000, v66
	v_mul_f32_e32 v0, v68, v68
	v_fma_f32 v0, v66, s10, -v0
	v_max_f32_e32 v0, 0, v0
	v_add_f32_e32 v0, 0x3727c5ac, v0
	s_mov_b32 s10, 0x800000
	v_cmp_gt_f32_e32 vcc, s10, v0
	v_mul_f32_e32 v66, 0x4b800000, v0
	s_nop 0
	v_cndmask_b32_e32 v0, v0, v66, vcc
	v_rsq_f32_e32 v0, v0
	s_nop 0
	v_mul_f32_e32 v66, 0x45800000, v0
	v_cndmask_b32_e32 v69, v0, v66, vcc
	s_cbranch_execz .LBB0_345
	s_branch .LBB0_346

; DI unsigned pack2(float a, float b) { fl2_t v = {a, b}; bf2_t r = __builtin_convertvector(v, bf2_t); return __builtin_bit_cast(unsigned, r); }
; DI float sigmoidf_(float x) { return __builtin_amdgcn_rcpf(1.f + __builtin_amdgcn_exp2f(-1.4426950408889634f * x)); }
; DI float rl(float v, int srclane) { return __int_as_float(__builtin_amdgcn_readlane(__float_as_int(v), srclane)); }
; DI void epi_rows(const Params& p, int L, int ekind, const float* T, int rbase, int bcol) {
;     ...
;       for (int i = 0; i < 16; ++i) {
;         const float mu = rl(mu_l, i), rstd = rl(rstd_l, i);
;         const float* tr = T + (lr0 + i) * TSTR + c;
;         float g0 = rstd * (tr[0] - mu * csg0) + bwg0, g1 = rstd * (tr[1] - mu * csg1) + bwg1;
;         float u0 = rstd * (tr[128] - mu * csu0) + bwu0, u1 = rstd * (tr[129] - mu * csu1) + bwu1;
;         float a0 = g0 * sigmoidf_(g0) * u0, a1 = g1 * sigmoidf_(g1) * u1;
;         stg<unsigned>(ap + (size_t)i * DFF, pack2(a0, a1));
;       }
; DI void epi_dispatch(const Params& p, int L, int ekind, f32x4 (&acc)[2][2][4][2], int brow, int bcol, int, int, int, int) {
;     ...
;   for (int ai = 0; ai < 2; ++ai) {
;     __syncthreads();
;     #pragma unroll
;     for (int bj = 0; bj < 2; ++bj)
;       #pragma unroll
;       for (int m = 0; m < 4; ++m)
;         #pragma unroll
;         for (int n = 0; n < 2; ++n)
;           #pragma unroll
;           for (int j = 0; j < 4; ++j) tw[(m * 16 + j) * TSTR + bj * 128 + n * 16] = acc[ai][bj][m][n][j];
;     __syncthreads();
.LBB0_347:
	ds_read2st64_b64 v[98:101], v87 offset1:1
	v_readlane_b32 s12, v68, s5
	v_readlane_b32 s24, v69, s5
	s_add_i32 s9, s5, 1
	s_waitcnt lgkmcnt(0)
	v_pk_fma_f32 v[88:89], v[70:71], s[12:13], v[98:99] op_sel_hi:[1,0,1] neg_lo:[1,0,0] neg_hi:[1,0,0]
	s_nop 0
	v_pk_fma_f32 v[88:89], s[24:25], v[88:89], v[74:75] op_sel_hi:[0,1,1]
	v_mul_f32_e32 v0, 0xbfb8aa3b, v88
	v_exp_f32_e32 v0, v0
	v_pk_fma_f32 v[92:93], v[72:73], s[12:13], v[100:101] op_sel_hi:[1,0,1] neg_lo:[1,0,0] neg_hi:[1,0,0]
	v_readlane_b32 s12, v68, s9
	v_pk_fma_f32 v[92:93], s[24:25], v[92:93], v[76:77] op_sel_hi:[0,1,1]
	v_add_f32_e32 v0, 1.0, v0
	v_rcp_f32_e32 v98, v0
	v_mul_f32_e32 v0, 0xbfb8aa3b, v89
	v_exp_f32_e32 v0, v0
	v_readlane_b32 s24, v69, s9
	s_add_i32 s9, s5, 2
	v_add_f32_e32 v0, 1.0, v0
	v_rcp_f32_e32 v99, v0
	s_nop 0
	v_pk_mul_f32 v[88:89], v[88:89], v[98:99]
	ds_read2_b64 v[98:101], v87 offset0:130 offset1:194
	v_pk_mul_f32 v[88:89], v[92:93], v[88:89]
	s_waitcnt lgkmcnt(0)
	v_pk_fma_f32 v[92:93], v[72:73], s[12:13], v[100:101] op_sel_hi:[1,0,1] neg_lo:[1,0,0] neg_hi:[1,0,0]
	v_cvt_pk_bf16_f32 v0, v88, v89
	v_add_co_u32_e32 v88, vcc, s22, v66
	v_pk_fma_f32 v[92:93], s[24:25], v[92:93], v[76:77] op_sel_hi:[0,1,1]
	s_nop 0
	v_addc_co_u32_e32 v89, vcc, -1, v67, vcc
	global_store_dword v[88:89], v0, off offset:-512
	v_pk_fma_f32 v[88:89], v[70:71], s[12:13], v[98:99] op_sel_hi:[1,0,1] neg_lo:[1,0,0] neg_hi:[1,0,0]
	v_readlane_b32 s12, v68, s9
	v_pk_fma_f32 v[88:89], s[24:25], v[88:89], v[74:75] op_sel_hi:[0,1,1]
	v_mul_f32_e32 v0, 0xbfb8aa3b, v88
	v_exp_f32_e32 v0, v0
	v_readlane_b32 s24, v69, s9
	s_add_i32 s9, s5, 3
	s_add_i32 s5, s5, 4
	v_add_f32_e32 v0, 1.0, v0
	v_rcp_f32_e32 v98, v0
	v_mul_f32_e32 v0, 0xbfb8aa3b, v89
	v_exp_f32_e32 v0, v0
	s_cmp_lg_u32 s5, 16
	v_add_f32_e32 v0, 1.0, v0
	v_rcp_f32_e32 v99, v0
	s_nop 0
	v_pk_mul_f32 v[88:89], v[88:89], v[98:99]
	s_nop 0
	v_pk_mul_f32 v[88:89], v[92:93], v[88:89]
	s_nop 0
	v_cvt_pk_bf16_f32 v0, v88, v89
	v_add_co_u32_e32 v88, vcc, s83, v66
	s_nop 1
	v_addc_co_u32_e32 v89, vcc, -1, v67, vcc
	global_store_dword v[88:89], v0, off offset:-3072
	v_add_u32_e32 v0, 32, v87
	ds_read2st64_b64 v[98:101], v0 offset0:4 offset1:5
	s_waitcnt lgkmcnt(0)
	v_pk_fma_f32 v[88:89], v[70:71], s[12:13], v[98:99] op_sel_hi:[1,0,1] neg_lo:[1,0,0] neg_hi:[1,0,0]
	s_nop 0
	v_pk_fma_f32 v[88:89], s[24:25], v[88:89], v[74:75] op_sel_hi:[0,1,1]
	v_mul_f32_e32 v0, 0xbfb8aa3b, v88
	v_exp_f32_e32 v0, v0
	v_pk_fma_f32 v[92:93], v[72:73], s[12:13], v[100:101] op_sel_hi:[1,0,1] neg_lo:[1,0,0] neg_hi:[1,0,0]
	v_readlane_b32 s12, v68, s9
	v_pk_fma_f32 v[92:93], s[24:25], v[92:93], v[76:77] op_sel_hi:[0,1,1]
	v_add_f32_e32 v0, 1.0, v0
	v_rcp_f32_e32 v98, v0
	v_mul_f32_e32 v0, 0xbfb8aa3b, v89
	v_exp_f32_e32 v0, v0
	v_readlane_b32 s24, v69, s9
	v_add_f32_e32 v0, 1.0, v0
	v_rcp_f32_e32 v99, v0
	s_nop 0
	v_pk_mul_f32 v[88:89], v[88:89], v[98:99]
	s_nop 0
	v_pk_mul_f32 v[88:89], v[92:93], v[88:89]
	s_nop 0
	v_cvt_pk_bf16_f32 v0, v88, v89
	v_add_co_u32_e32 v88, vcc, s84, v66
	s_nop 1
	v_addc_co_u32_e32 v89, vcc, -1, v67, vcc
	global_store_dword v[88:89], v0, off offset:-1536
	v_add_u32_e32 v0, 48, v87
	ds_read2st64_b64 v[98:101], v0 offset0:6 offset1:7
	v_add_u32_e32 v87, 0x1040, v87
	s_waitcnt lgkmcnt(0)
	v_pk_fma_f32 v[88:89], v[70:71], s[12:13], v[98:99] op_sel_hi:[1,0,1] neg_lo:[1,0,0] neg_hi:[1,0,0]
	s_nop 0
	v_pk_fma_f32 v[88:89], s[24:25], v[88:89], v[74:75] op_sel_hi:[0,1,1]
	v_mul_f32_e32 v0, 0xbfb8aa3b, v88
	v_exp_f32_e32 v0, v0
	v_pk_fma_f32 v[92:93], v[72:73], s[12:13], v[100:101] op_sel_hi:[1,0,1] neg_lo:[1,0,0] neg_hi:[1,0,0]
	v_add_f32_e32 v0, 1.0, v0
	v_rcp_f32_e32 v98, v0
	v_mul_f32_e32 v0, 0xbfb8aa3b, v89
	v_exp_f32_e32 v0, v0
	v_pk_fma_f32 v[92:93], s[24:25], v[92:93], v[76:77] op_sel_hi:[0,1,1]
	v_add_f32_e32 v0, 1.0, v0
	v_rcp_f32_e32 v99, v0
	s_nop 0
	v_pk_mul_f32 v[88:89], v[88:89], v[98:99]
	s_nop 0
	v_pk_mul_f32 v[88:89], v[92:93], v[88:89]
	s_nop 0
	v_cvt_pk_bf16_f32 v0, v88, v89
	global_store_dword v[66:67], v0, off
	v_lshl_add_u64 v[66:67], v[66:67], 0, s[88:89]
	s_cbranch_scc1 .LBB0_347
	s_barrier
	ds_write2_b32 v130, v2, v18 offset1:16
	ds_write2_b32 v114, v3, v19 offset0:4 offset1:20
	ds_write2_b32 v115, v4, v20 offset0:8 offset1:24
	ds_write2_b32 v116, v5, v21 offset0:12 offset1:28
	ds_write2_b32 v117, v6, v22 offset0:64 offset1:80
	ds_write2_b32 v82, v7, v23 offset0:68 offset1:84
	ds_write2_b32 v83, v8, v24 offset0:72 offset1:88
	ds_write2_b32 v84, v9, v25 offset0:76 offset1:92
	ds_write2_b32 v96, v10, v26 offset0:128 offset1:144
	ds_write2_b32 v85, v11, v27 offset0:132 offset1:148
	ds_write2_b32 v79, v12, v28 offset0:136 offset1:152
	ds_write2_b32 v80, v13, v29 offset0:140 offset1:156
	ds_write2_b32 v97, v14, v30 offset0:192 offset1:208
	ds_write2_b32 v81, v15, v31 offset0:196 offset1:212
	ds_write2_b32 v94, v16, v32 offset0:200 offset1:216
	ds_write2_b32 v95, v17, v33 offset0:204 offset1:220
	ds_write2_b32 v130, v34, v50 offset0:128 offset1:144
	ds_write2_b32 v114, v35, v51 offset0:132 offset1:148
	ds_write2_b32 v115, v36, v52 offset0:136 offset1:152
	ds_write2_b32 v116, v37, v53 offset0:140 offset1:156
	ds_write2_b32 v117, v38, v54 offset0:192 offset1:208
	ds_write2_b32 v82, v39, v55 offset0:196 offset1:212
	ds_write2_b32 v83, v40, v56 offset0:200 offset1:216
	ds_write2_b32 v84, v41, v57 offset0:204 offset1:220
	ds_write2_b32 v85, v42, v58 offset1:16
	ds_write2_b32 v79, v43, v59 offset0:4 offset1:20
	ds_write2_b32 v80, v44, v60 offset0:8 offset1:24
	ds_write2_b32 v90, v45, v61 offset0:12 offset1:28
	ds_write2_b32 v81, v46, v62 offset0:64 offset1:80
	ds_write2_b32 v94, v47, v63 offset0:68 offset1:84
	ds_write2_b32 v95, v48, v64 offset0:72 offset1:88
	ds_write2_b32 v86, v49, v65 offset0:76 offset1:92
	s_mov_b64 s[12:13], s[70:71]
	v_mov_b32_e32 v15, v178
	s_waitcnt lgkmcnt(0)
	s_barrier
; DI float fxc(const i64* p) { return (float)(*p) * FXC_INV; }
; DI RowStat row_stat(const i64* st, int row) {
;   float s = (float)st[2 * (size_t)row] * FXS_INV, q = (float)st[2 * (size_t)row + 1] * FXS_INV;
;   float mu = s * (1.f / 1024.f);
;   float var = fmaxf(q * (1.f / 1024.f) - mu * mu, 0.f);
;   RowStat r; r.mu = mu; r.rstd = rsqrtf(var + 1e-5f); return r;
; DI void epi_rows(const Params& p, int L, int ekind, const float* T, int rbase, int bcol) {
;     ...
;       if (st) { const i64* q = cs + co + bcol + c; const i64* r = bw + co + bcol + c;
;         csg0 = fxc(q); csg1 = fxc(q + 1); csu0 = fxc(q + 128); csu1 = fxc(q + 129); bwg0 = fxc(r); bwg1 = fxc(r + 1); bwu0 = fxc(r + 128); bwu1 = fxc(r + 129);
;         RowStat rs = row_stat(st, myrow); mu_l = rs.mu; rstd_l = rs.rstd; }
	v_readlane_b32 s24, v254, 5
	v_readfirstlane_b32 s5, v15
	s_ashr_i32 s9, s5, 2
	v_lshlrev_b32_e32 v0, 1, v15
	v_readlane_b32 s25, v254, 6
	s_and_b32 s5, s9, -16
	s_andn2_b64 vcc, exec, s[24:25]
	v_and_b32_e32 v14, 0x7e, v0
	s_cbranch_vccnz .LBB0_350
	v_readlane_b32 s24, v255, 12
	v_readlane_b32 s25, v255, 13
	s_add_i32 s8, s5, s8
	s_lshl_b64 s[24:25], s[24:25], 3
	v_and_or_b32 v2, v15, 15, s8
	s_add_u32 s8, s12, s24
	s_addc_u32 s19, s13, s25
	s_lshl_b64 s[6:7], s[6:7], 3
	s_add_u32 s6, s8, s6
	s_addc_u32 s7, s19, s7
	v_lshlrev_b32_e32 v0, 3, v14
	v_lshl_add_u64 v[10:11], s[6:7], 0, v[0:1]
	s_mov_b64 s[6:7], 0x38e000
	v_lshl_add_u64 v[12:13], v[10:11], 0, s[6:7]
	s_mov_b64 s[6:7], 0x3c9000
	v_lshl_add_u64 v[4:5], v[10:11], 0, s[6:7]
	s_mov_b32 s6, 0x38e000
	v_add_co_u32_e32 v6, vcc, s6, v10
	flat_load_dwordx4 v[16:19], v[12:13] offset:1024
	s_nop 0
	v_addc_co_u32_e32 v7, vcc, 0, v11, vcc
	flat_load_dwordx4 v[6:9], v[6:7]
	s_mov_b32 s8, 0x2f800000
	s_mov_b32 s6, 0x3c9000
	v_add_co_u32_e32 v10, vcc, s6, v10
	s_mov_b32 s6, 0x104000
	s_nop 0
	v_addc_co_u32_e32 v11, vcc, 0, v11, vcc
	flat_load_dwordx4 v[188:191], v[10:11]
	flat_load_dwordx4 v[196:199], v[4:5] offset:1024
	v_mov_b32_e32 v208, v2
	v_ashrrev_i32_e32 v209, 31, v208
	v_lshl_add_u64 v[208:209], v[208:209], 4, s[12:13]
	v_add_co_u32_e32 v208, vcc, s6, v208
	s_nop 1
	v_addc_co_u32_e32 v209, vcc, 0, v209, vcc
	flat_load_dwordx4 v[204:207], v[208:209]
	s_waitcnt vmcnt(0) lgkmcnt(0)
	v_xor_b32_e32 v0, v8, v9
	v_ashrrev_i32_e32 v0, 31, v0
	v_ffbh_i32_e32 v3, v9
	v_add_u32_e32 v0, 32, v0
	v_add_u32_e32 v3, -1, v3
	v_min_u32_e32 v0, v3, v0
	v_lshlrev_b64 v[8:9], v0, v[8:9]
	v_min_u32_e32 v3, 1, v8
	v_or_b32_e32 v3, v9, v3
	v_cvt_f32_i32_e32 v3, v3
	v_sub_u32_e32 v0, 32, v0
	v_ldexp_f32 v9, v3, v0
	v_xor_b32_e32 v0, v6, v7
	v_ashrrev_i32_e32 v0, 31, v0
	v_ffbh_i32_e32 v3, v7
	v_add_u32_e32 v0, 32, v0
	v_add_u32_e32 v3, -1, v3
	v_min_u32_e32 v0, v3, v0
	v_lshlrev_b64 v[6:7], v0, v[6:7]
	v_min_u32_e32 v3, 1, v6
	v_or_b32_e32 v3, v7, v3
	v_cvt_f32_i32_e32 v3, v3
	v_sub_u32_e32 v0, 32, v0
	v_ldexp_f32 v8, v3, v0
	v_xor_b32_e32 v0, v18, v19
	v_ashrrev_i32_e32 v0, 31, v0
	v_ffbh_i32_e32 v3, v19
	v_add_u32_e32 v0, 32, v0
	v_add_u32_e32 v3, -1, v3
	v_min_u32_e32 v0, v3, v0
	v_pk_mul_f32 v[6:7], v[8:9], s[8:9] op_sel_hi:[1,0]
	v_lshlrev_b64 v[8:9], v0, v[18:19]
	v_min_u32_e32 v3, 1, v8
	v_or_b32_e32 v3, v9, v3
	v_cvt_f32_i32_e32 v3, v3
	v_sub_u32_e32 v0, 32, v0
	v_ldexp_f32 v9, v3, v0
	v_xor_b32_e32 v0, v16, v17
	v_ashrrev_i32_e32 v0, 31, v0
	v_ffbh_i32_e32 v3, v17
	v_add_u32_e32 v0, 32, v0
	v_add_u32_e32 v3, -1, v3
	v_min_u32_e32 v0, v3, v0
	v_lshlrev_b64 v[12:13], v0, v[16:17]
	v_min_u32_e32 v3, 1, v12
	v_or_b32_e32 v3, v13, v3
	v_mov_b64_e32 v[10:11], v[188:189]
	v_mov_b64_e32 v[12:13], v[190:191]
	v_cvt_f32_i32_e32 v3, v3
	v_mov_b64_e32 v[16:17], v[196:197]
	v_mov_b64_e32 v[18:19], v[198:199]
	v_sub_u32_e32 v0, 32, v0
	v_ldexp_f32 v8, v3, v0
	v_pk_mul_f32 v[8:9], v[8:9], s[8:9] op_sel_hi:[1,0]
	s_waitcnt vmcnt(0) lgkmcnt(0)
	v_xor_b32_e32 v0, v12, v13
	v_ashrrev_i32_e32 v0, 31, v0
	v_ffbh_i32_e32 v3, v13
	v_add_u32_e32 v0, 32, v0
	v_add_u32_e32 v3, -1, v3
	v_min_u32_e32 v0, v3, v0
	v_lshlrev_b64 v[12:13], v0, v[12:13]
	v_min_u32_e32 v3, 1, v12
	v_or_b32_e32 v3, v13, v3
	v_cvt_f32_i32_e32 v3, v3
	v_sub_u32_e32 v0, 32, v0
	v_ldexp_f32 v13, v3, v0
	v_xor_b32_e32 v0, v10, v11
	v_ashrrev_i32_e32 v0, 31, v0
	v_ffbh_i32_e32 v3, v11
	v_add_u32_e32 v0, 32, v0
	v_add_u32_e32 v3, -1, v3
	v_min_u32_e32 v0, v3, v0
	v_lshlrev_b64 v[10:11], v0, v[10:11]
	v_min_u32_e32 v3, 1, v10
	v_or_b32_e32 v3, v11, v3
	v_cvt_f32_i32_e32 v3, v3
	v_sub_u32_e32 v0, 32, v0
	v_ldexp_f32 v12, v3, v0
	v_xor_b32_e32 v0, v18, v19
	v_ashrrev_i32_e32 v0, 31, v0
	v_ffbh_i32_e32 v3, v19
	v_add_u32_e32 v0, 32, v0
	v_add_u32_e32 v3, -1, v3
	v_min_u32_e32 v0, v3, v0
	v_lshlrev_b64 v[4:5], v0, v[18:19]
	v_min_u32_e32 v3, 1, v4
	v_or_b32_e32 v3, v5, v3
	v_cvt_f32_i32_e32 v3, v3
	v_sub_u32_e32 v0, 32, v0
	v_pk_mul_f32 v[10:11], v[12:13], s[8:9] op_sel_hi:[1,0]
	v_ldexp_f32 v5, v3, v0
	v_xor_b32_e32 v0, v16, v17
	v_ashrrev_i32_e32 v0, 31, v0
	v_ffbh_i32_e32 v3, v17
	v_add_u32_e32 v0, 32, v0
	v_add_u32_e32 v3, -1, v3
	v_min_u32_e32 v0, v3, v0
	v_lshlrev_b64 v[12:13], v0, v[16:17]
	v_min_u32_e32 v3, 1, v12
	v_or_b32_e32 v3, v13, v3
	v_cvt_f32_i32_e32 v3, v3
	v_sub_u32_e32 v0, 32, v0
	v_ldexp_f32 v4, v3, v0
	v_ashrrev_i32_e32 v3, 31, v2
	v_lshl_add_u64 v[2:3], v[2:3], 4, s[12:13]
	v_add_co_u32_e32 v2, vcc, s6, v2
	v_pk_mul_f32 v[12:13], v[4:5], s[8:9] op_sel_hi:[1,0]
	s_nop 0
	v_addc_co_u32_e32 v3, vcc, 0, v3, vcc
	v_mov_b64_e32 v[2:3], v[204:205]
	v_mov_b64_e32 v[4:5], v[206:207]
	s_mov_b32 s6, 0x3a800000
	s_waitcnt vmcnt(0) lgkmcnt(0)
	v_xor_b32_e32 v0, v2, v3
	v_ashrrev_i32_e32 v0, 31, v0
	v_ffbh_i32_e32 v16, v3
	v_add_u32_e32 v0, 32, v0
	v_add_u32_e32 v16, -1, v16
	v_min_u32_e32 v0, v16, v0
	v_lshlrev_b64 v[2:3], v0, v[2:3]
	v_min_u32_e32 v2, 1, v2
	v_or_b32_e32 v2, v3, v2
	v_cvt_f32_i32_e32 v2, v2
	v_sub_u32_e32 v0, 32, v0
	v_ffbh_i32_e32 v3, v5
	v_add_u32_e32 v3, -1, v3
	v_ldexp_f32 v0, v2, v0
	v_xor_b32_e32 v2, v4, v5
	v_ashrrev_i32_e32 v2, 31, v2
	v_add_u32_e32 v2, 32, v2
	v_min_u32_e32 v16, v3, v2
	v_lshlrev_b64 v[2:3], v16, v[4:5]
	v_min_u32_e32 v2, 1, v2
	v_or_b32_e32 v2, v3, v2
	v_cvt_f32_i32_e32 v2, v2
	v_mul_f32_e32 v0, 0x33800000, v0
	v_sub_u32_e32 v3, 32, v16
	v_mul_f32_e32 v4, 0x3a800000, v0
	v_ldexp_f32 v2, v2, v3
	v_mul_f32_e32 v2, 0x33800000, v2
	v_mul_f32_e32 v0, v4, v4
	v_fma_f32 v0, v2, s6, -v0
	v_max_f32_e32 v0, 0, v0
	v_add_f32_e32 v0, 0x3727c5ac, v0
	s_mov_b32 s6, 0x800000
	v_cmp_gt_f32_e32 vcc, s6, v0
	v_mul_f32_e32 v2, 0x4b800000, v0
	s_nop 0
	v_cndmask_b32_e32 v0, v0, v2, vcc
	v_rsq_f32_e32 v0, v0
	s_nop 0
	v_mul_f32_e32 v2, 0x45800000, v0
	v_cndmask_b32_e32 v5, v0, v2, vcc
	s_cbranch_execz .LBB0_351
	s_branch .LBB0_352

; DI float fxc(const i64* p) { return (float)(*p) * FXC_INV; }
; DI void epi_rows(const Params& p, int L, int ekind, const float* T, int rbase, int bcol) {
;     ...
;       const i64* st = ST_(L, 0); const int co = a ? CS_WGA : CS_WGB;
;       const size_t off0 = (size_t)(rbase + lr0) * 1024 + bcol + c4;
;       const u16* src = (const u16*)(R + (a ? R_MX : R_GT)) + off0; u16* Mx = (u16*)(R + R_MX) + off0;
;       f32x4 cs4, bw4;
;       for (int k = 0; k < 4; ++k) { cs4[k] = fxc(cs + co + bcol + c4 + k); bw4[k] = fxc(bw + co + bcol + c4 + k); }
;       RowStat rs_l = row_stat(st, myrow);
; DI void epi_dispatch(const Params& p, int L, int ekind, f32x4 (&acc)[2][2][4][2], int brow, int bcol, int, int, int, int) {
;     ...
;   for (int ai = 0; ai < 2; ++ai) {
;     __syncthreads();
;     #pragma unroll
;     for (int bj = 0; bj < 2; ++bj)
;       #pragma unroll
;       for (int m = 0; m < 4; ++m)
;         #pragma unroll
;         for (int n = 0; n < 2; ++n)
;           #pragma unroll
;           for (int j = 0; j < 4; ++j) tw[(m * 16 + j) * TSTR + bj * 128 + n * 16] = acc[ai][bj][m][n][j];
;     __syncthreads();
.LBB0_1744:
	s_or_b64 exec, exec, s[10:11]
	v_mov_b32_e32 v0, v178
	s_movk_i32 s9, 0x410
	v_lshrrev_b32_e32 v131, 2, v0
	v_and_b32_e32 v131, 0xfffffcc, v131
	v_and_b32_e32 v130, 15, v0
	v_mul_lo_u32 v131, v131, s9
	v_lshlrev_b32_e32 v0, 1, v0
	v_add_u32_e32 v131, 0, v131
	v_and_b32_e32 v0, 0x180, v0
	v_lshlrev_b32_e32 v130, 2, v130
	v_add3_u32 v130, v131, v0, v130
	s_waitcnt vmcnt(0)
	s_barrier
	ds_write2_b32 v130, v114, v126 offset1:16
	v_add_u32_e32 v114, 0x400, v130
	ds_write2_b32 v114, v115, v127 offset0:4 offset1:20
	v_add_u32_e32 v115, 0x800, v130
	ds_write2_b32 v115, v116, v128 offset0:8 offset1:24
	v_add_u32_e32 v116, 0xc00, v130
	ds_write2_b32 v116, v117, v129 offset0:12 offset1:28
	v_add_u32_e32 v117, 0x4000, v130
	ds_write2_b32 v117, v82, v94 offset0:64 offset1:80
	v_add_u32_e32 v82, 0x4400, v130
	ds_write2_b32 v82, v83, v95 offset0:68 offset1:84
	v_add_u32_e32 v83, 0x4800, v130
	ds_write2_b32 v83, v84, v96 offset0:72 offset1:88
	v_add_u32_e32 v84, 0x4c00, v130
	ds_write2_b32 v84, v85, v97 offset0:76 offset1:92
	v_add_u32_e32 v127, 0x8000, v130
	v_add_u32_e32 v85, 0x8400, v130
	v_add_u32_e32 v94, 0x8800, v130
	v_add_u32_e32 v95, 0x8c00, v130
	v_add_u32_e32 v128, 0xc000, v130
	v_add_u32_e32 v96, 0xc400, v130
	v_add_u32_e32 v97, 0xc800, v130
	v_add_u32_e32 v126, 0xcc00, v130
	v_readlane_b32 s12, v254, 25
	v_readlane_b32 s10, v255, 12
	ds_write2_b32 v127, v74, v78 offset0:128 offset1:144
	ds_write2_b32 v85, v75, v79 offset0:132 offset1:148
	ds_write2_b32 v94, v76, v80 offset0:136 offset1:152
	ds_write2_b32 v95, v77, v81 offset0:140 offset1:156
	ds_write2_b32 v128, v66, v70 offset0:192 offset1:208
	ds_write2_b32 v96, v67, v71 offset0:196 offset1:212
	ds_write2_b32 v97, v68, v72 offset0:200 offset1:216
	ds_write2_b32 v126, v69, v73 offset0:204 offset1:220
	ds_write2_b32 v130, v98, v118 offset0:128 offset1:144
	ds_write2_b32 v114, v99, v119 offset0:132 offset1:148
	ds_write2_b32 v115, v100, v120 offset0:136 offset1:152
	ds_write2_b32 v116, v101, v121 offset0:140 offset1:156
	ds_write2_b32 v117, v102, v122 offset0:192 offset1:208
	ds_write2_b32 v82, v103, v123 offset0:196 offset1:212
	ds_write2_b32 v83, v104, v124 offset0:200 offset1:216
	ds_write2_b32 v84, v105, v125 offset0:204 offset1:220
	ds_write2_b32 v85, v90, v110 offset1:16
	ds_write2_b32 v94, v91, v111 offset0:4 offset1:20
	ds_write2_b32 v95, v92, v112 offset0:8 offset1:24
	v_add_u32_e32 v90, 0x9000, v130
	v_readlane_b32 s13, v254, 26
	v_readlane_b32 s14, v254, 27
	v_readlane_b32 s15, v254, 28
	v_readlane_b32 s11, v255, 13
	ds_write2_b32 v90, v93, v113 offset0:12 offset1:28
	ds_write2_b32 v96, v86, v106 offset0:64 offset1:80
	ds_write2_b32 v97, v87, v107 offset0:68 offset1:84
	ds_write2_b32 v126, v88, v108 offset0:72 offset1:88
	v_add_u32_e32 v86, 0xd000, v130
	s_mov_b64 s[68:69], s[14:15]
	v_mov_b32_e32 v0, v178
	s_lshl_b64 s[12:13], s[10:11], 3
	ds_write2_b32 v86, v89, v109 offset0:76 offset1:92
	s_waitcnt lgkmcnt(0)
	s_barrier
	s_add_u32 s14, s68, s12
	v_readfirstlane_b32 s9, v0
	s_addc_u32 s15, s69, s13
	s_ashr_i32 s9, s9, 2
	s_and_b32 s9, s9, -16
	v_lshlrev_b32_e32 v66, 2, v0
	v_and_b32_e32 v74, 0xfc, v66
	s_add_i32 s10, s9, s16
	v_and_or_b32 v66, v0, 15, s10
	v_lshlrev_b32_e32 v0, 1, v74
	s_ashr_i32 s11, s10, 31
	v_lshl_add_u64 v[68:69], s[68:69], 0, v[0:1]
	v_lshl_add_u64 v[68:69], s[6:7], 1, v[68:69]
	s_lshl_b64 s[10:11], s[10:11], 11
	v_lshl_add_u64 v[68:69], v[68:69], 0, s[10:11]
	s_mov_b64 s[10:11], 0xa0cda00
	v_lshl_add_u64 v[70:71], v[68:69], 0, s[10:11]
	s_lshl_b64 s[10:11], s[6:7], 3
	s_add_u32 s14, s14, s10
	v_lshlrev_b32_e32 v0, 3, v74
	s_addc_u32 s15, s15, s11
	v_lshl_add_u64 v[80:81], s[14:15], 0, v[0:1]
	s_mov_b64 s[14:15], 0x39c800
	v_lshl_add_u64 v[72:73], v[80:81], 0, s[14:15]
	s_mov_b64 s[14:15], 0x3d7800
	v_lshl_add_u64 v[68:69], v[80:81], 0, s[14:15]
	s_mov_b32 s14, 0x39c000
	v_add_co_u32_e32 v76, vcc, s14, v80
	s_mov_b32 s14, 0x3d7000
	s_nop 0
	v_addc_co_u32_e32 v77, vcc, 0, v81, vcc
	flat_load_dwordx4 v[76:79], v[76:77] offset:2048
	s_mov_b32 s50, 0x3a800000
	s_mov_b32 s17, 0
	v_add_co_u32_e32 v192, vcc, s14, v80
	s_nop 1
	v_addc_co_u32_e32 v193, vcc, 0, v81, vcc
	flat_load_dwordx4 v[188:191], v[192:193] offset:2048
	flat_load_dwordx4 v[196:199], v[72:73] offset:16
	flat_load_dwordx4 v[204:207], v[68:69] offset:16
	s_waitcnt vmcnt(0) lgkmcnt(0)
	v_xor_b32_e32 v0, v76, v77
	v_ashrrev_i32_e32 v0, 31, v0
	v_ffbh_i32_e32 v67, v77
	v_add_u32_e32 v0, 32, v0
	v_add_u32_e32 v67, -1, v67
	v_min_u32_e32 v0, v67, v0
	v_lshlrev_b64 v[76:77], v0, v[76:77]
	v_min_u32_e32 v67, 1, v76
	v_add_co_u32_e32 v76, vcc, s14, v80
	v_or_b32_e32 v67, v77, v67
	s_nop 0
	v_addc_co_u32_e32 v77, vcc, 0, v81, vcc
	v_mov_b64_e32 v[98:99], v[188:189]
	v_mov_b64_e32 v[100:101], v[190:191]
	v_cvt_f32_i32_e32 v67, v67
	v_sub_u32_e32 v0, 32, v0
	v_readlane_b32 s14, v254, 1
	v_readlane_b32 s15, v254, 2
	v_ldexp_f32 v0, v67, v0
	s_lshl_b64 s[14:15], s[14:15], 3
	s_add_u32 s68, s68, s14
	s_addc_u32 s69, s69, s15
	v_mul_f32_e32 v0, 0x2f800000, v0
	s_waitcnt vmcnt(0) lgkmcnt(0)
; DI float fxc(const i64* p) { return (float)(*p) * FXC_INV; }
; DI RowStat row_stat(const i64* st, int row) {
;   float s = (float)st[2 * (size_t)row] * FXS_INV, q = (float)st[2 * (size_t)row + 1] * FXS_INV;
;   float mu = s * (1.f / 1024.f);
;   float var = fmaxf(q * (1.f / 1024.f) - mu * mu, 0.f);
;   RowStat r; r.mu = mu; r.rstd = rsqrtf(var + 1e-5f); return r;
; DI void epi_rows(const Params& p, int L, int ekind, const float* T, int rbase, int bcol) {
;     ...
;       for (int k = 0; k < 4; ++k) { cs4[k] = fxc(cs + CS_WIN + cg + k); bw4[k] = fxc(bw + CS_WIN + cg + k); }
	v_xor_b32_e32 v67, v98, v99
	v_ashrrev_i32_e32 v67, 31, v67
	v_ffbh_i32_e32 v75, v99
	v_add_u32_e32 v67, 32, v67
	v_add_u32_e32 v75, -1, v75
	v_min_u32_e32 v67, v75, v67
	v_lshlrev_b64 v[76:77], v67, v[98:99]
	v_min_u32_e32 v75, 1, v76
	v_or_b32_e32 v75, v77, v75
	v_cvt_f32_i32_e32 v75, v75
	v_sub_u32_e32 v67, 32, v67
	v_ldexp_f32 v67, v75, v67
	v_mul_f32_e32 v87, 0x2f800000, v67
	v_xor_b32_e32 v67, v78, v79
	v_ashrrev_i32_e32 v67, 31, v67
	v_ffbh_i32_e32 v75, v79
	v_add_u32_e32 v67, 32, v67
	v_add_u32_e32 v75, -1, v75
	v_min_u32_e32 v67, v75, v67
	v_lshlrev_b64 v[76:77], v67, v[78:79]
	v_min_u32_e32 v75, 1, v76
	v_or_b32_e32 v75, v77, v75
	v_cvt_f32_i32_e32 v75, v75
	v_sub_u32_e32 v67, 32, v67
	v_ldexp_f32 v67, v75, v67
	v_mul_f32_e32 v88, 0x2f800000, v67
	v_xor_b32_e32 v67, v100, v101
	v_ashrrev_i32_e32 v67, 31, v67
	v_ffbh_i32_e32 v75, v101
	v_add_u32_e32 v67, 32, v67
	v_add_u32_e32 v75, -1, v75
	v_min_u32_e32 v67, v75, v67
	v_lshlrev_b64 v[76:77], v67, v[100:101]
	v_min_u32_e32 v75, 1, v76
	v_or_b32_e32 v75, v77, v75
	v_mov_b64_e32 v[76:77], v[196:197]
	v_mov_b64_e32 v[78:79], v[198:199]
	v_mov_b64_e32 v[98:99], v[204:205]
	v_mov_b64_e32 v[100:101], v[206:207]
	v_cvt_f32_i32_e32 v75, v75
	v_sub_u32_e32 v67, 32, v67
	v_ldexp_f32 v67, v75, v67
	v_mul_f32_e32 v89, 0x2f800000, v67
	s_waitcnt vmcnt(0) lgkmcnt(0)
	v_xor_b32_e32 v67, v76, v77
	v_ashrrev_i32_e32 v67, 31, v67
	v_ffbh_i32_e32 v72, v77
	v_add_u32_e32 v67, 32, v67
	v_add_u32_e32 v72, -1, v72
	v_min_u32_e32 v67, v72, v67
	v_lshlrev_b64 v[72:73], v67, v[76:77]
	v_min_u32_e32 v72, 1, v72
	v_or_b32_e32 v72, v73, v72
	v_cvt_f32_i32_e32 v72, v72
	v_sub_u32_e32 v67, 32, v67
	v_ffbh_i32_e32 v68, v99
	v_add_u32_e32 v68, -1, v68
	v_ldexp_f32 v67, v72, v67
	v_mul_f32_e32 v91, 0x2f800000, v67
	v_xor_b32_e32 v67, v98, v99
	v_ashrrev_i32_e32 v67, 31, v67
	v_add_u32_e32 v67, 32, v67
	v_min_u32_e32 v67, v68, v67
	v_lshlrev_b64 v[68:69], v67, v[98:99]
	v_min_u32_e32 v68, 1, v68
	v_or_b32_e32 v68, v69, v68
	v_cvt_f32_i32_e32 v68, v68
	v_sub_u32_e32 v67, 32, v67
	v_ldexp_f32 v67, v68, v67
	v_mul_f32_e32 v92, 0x2f800000, v67
	v_xor_b32_e32 v67, v78, v79
	v_ashrrev_i32_e32 v67, 31, v67
	v_ffbh_i32_e32 v68, v79
	v_add_u32_e32 v67, 32, v67
	v_add_u32_e32 v68, -1, v68
	v_min_u32_e32 v67, v68, v67
	v_lshlrev_b64 v[68:69], v67, v[78:79]
	v_min_u32_e32 v68, 1, v68
	v_or_b32_e32 v68, v69, v68
	v_cvt_f32_i32_e32 v68, v68
	v_sub_u32_e32 v67, 32, v67
	v_ldexp_f32 v67, v68, v67
	v_mul_f32_e32 v93, 0x2f800000, v67
	v_xor_b32_e32 v67, v100, v101
	v_ashrrev_i32_e32 v67, 31, v67
	v_ffbh_i32_e32 v68, v101
	v_add_u32_e32 v67, 32, v67
	v_add_u32_e32 v68, -1, v68
	v_min_u32_e32 v67, v68, v67
	v_lshlrev_b64 v[68:69], v67, v[100:101]
	v_min_u32_e32 v68, 1, v68
	v_or_b32_e32 v68, v69, v68
	v_cvt_f32_i32_e32 v68, v68
	v_sub_u32_e32 v67, 32, v67
	v_lshl_add_u32 v101, v74, 2, 0
	v_ldexp_f32 v67, v68, v67
	v_mul_f32_e32 v98, 0x2f800000, v67
	v_ashrrev_i32_e32 v67, 31, v66
	v_lshl_add_u64 v[66:67], v[66:67], 4, s[68:69]
	flat_load_dwordx4 v[66:69], v[66:67]
	s_mov_b64 s[68:69], -1
	s_waitcnt vmcnt(0) lgkmcnt(0)
	v_xor_b32_e32 v72, v66, v67
	v_ashrrev_i32_e32 v72, 31, v72
	v_ffbh_i32_e32 v73, v67
	v_add_u32_e32 v72, 32, v72
	v_add_u32_e32 v73, -1, v73
	v_min_u32_e32 v72, v73, v72
	v_lshlrev_b64 v[66:67], v72, v[66:67]
	v_min_u32_e32 v66, 1, v66
	v_or_b32_e32 v66, v67, v66
	v_cvt_f32_i32_e32 v66, v66
	v_sub_u32_e32 v67, 32, v72
	v_ldexp_f32 v66, v66, v67
	v_mul_f32_e32 v72, 0x33800000, v66
	v_xor_b32_e32 v66, v68, v69
	v_ashrrev_i32_e32 v66, 31, v66
	v_ffbh_i32_e32 v67, v69
	v_add_u32_e32 v66, 32, v66
	v_add_u32_e32 v67, -1, v67
	v_min_u32_e32 v73, v67, v66
	v_lshlrev_b64 v[66:67], v73, v[68:69]
	v_min_u32_e32 v66, 1, v66
	v_or_b32_e32 v66, v67, v66
	v_cvt_f32_i32_e32 v66, v66
	v_sub_u32_e32 v67, 32, v73
	v_mul_f32_e32 v99, 0x3a800000, v72
	v_ldexp_f32 v66, v66, v67
	v_mul_f32_e32 v66, 0x33800000, v66
	v_mul_f32_e32 v67, v99, v99
	v_fma_f32 v66, v66, s50, -v67
	v_max_f32_e32 v66, 0, v66
	v_add_f32_e32 v66, 0x3727c5ac, v66
	s_mov_b32 s50, 0x800000
	v_cmp_gt_f32_e32 vcc, s50, v66
	v_mul_f32_e32 v67, 0x4b800000, v66
	s_nop 0
	v_cndmask_b32_e32 v66, v66, v67, vcc
	v_rsq_f32_e32 v66, v66
	s_nop 0
	v_mul_f32_e32 v67, 0x45800000, v66
	v_cndmask_b32_e32 v100, v66, v67, vcc
; DI unsigned pack2(float a, float b) { fl2_t v = {a, b}; bf2_t r = __builtin_convertvector(v, bf2_t); return __builtin_bit_cast(unsigned, r); }
; DI float bflo(unsigned u) { return __uint_as_float(u << 16); }
; DI float bfhi(unsigned u) { return __uint_as_float(u & 0xffff0000u); }
; DI float sigmoidf_(float x) { return __builtin_amdgcn_rcpf(1.f + __builtin_amdgcn_exp2f(-1.4426950408889634f * x)); }
; DI float rl(float v, int srclane) { return __int_as_float(__builtin_amdgcn_readlane(__float_as_int(v), srclane)); }
; DI void epi_rows(const Params& p, int L, int ekind, const float* T, int rbase, int bcol) {
;     ...
;       #pragma unroll 1
;       for (int ch = 0; ch < 2; ++ch) {
;         u32x2 sv[8], mv[8];
;         #pragma unroll
;         for (int i = 0; i < 8; ++i) {
;           sv[i] = ldg<u32x2>(src + (size_t)(ch * 8 + i) * 1024);
;           if (!a) mv[i] = ldg<u32x2>(Mx + (size_t)(ch * 8 + i) * 1024);
;         }
;         #pragma unroll
;         for (int i = 0; i < 8; ++i) {
;           const int ri = ch * 8 + i;
;           const float mu = rl(rs_l.mu, ri), rstd = rl(rs_l.rstd, ri);
;           f32x4 t = *(const f32x4*)(T + (lr0 + ri) * TSTR + c4);
;           float sf[4] = {bflo(sv[i][0]), bfhi(sv[i][0]), bflo(sv[i][1]), bfhi(sv[i][1])};
;           float v[4];
;           for (int k = 0; k < 4; ++k) v[k] = sigmoidf_(rstd * (t[k] - mu * cs4[k]) + bw4[k]) * sf[k];
;           if (!a) { v[0] += bflo(mv[i][0]); v[1] += bfhi(mv[i][0]); v[2] += bflo(mv[i][1]); v[3] += bfhi(mv[i][1]); }
;           u32x2 o; o[0] = pack2(v[0], v[1]); o[1] = pack2(v[2], v[3]);
;           stg<u32x2>(Mx + (size_t)ri * 1024, o);
.LBB0_1745:
	s_lshl_b32 s50, s17, 14
	v_lshl_add_u64 v[106:107], v[70:71], 0, s[50:51]
	global_load_dwordx2 v[108:109], v[106:107], off
	global_load_dwordx2 v[80:81], v[106:107], off offset:2048
	v_add_co_u32_e32 v66, vcc, 0x1000, v106
	s_waitcnt vmcnt(1)
	v_lshlrev_b32_e32 v110, 16, v108
	v_addc_co_u32_e32 v67, vcc, 0, v107, vcc
	global_load_dwordx2 v[78:79], v[66:67], off
	global_load_dwordx2 v[76:77], v[66:67], off offset:2048
	v_add_co_u32_e32 v66, vcc, 0x2000, v106
	v_and_b32_e32 v111, 0xffff0000, v108
	s_nop 0
	v_addc_co_u32_e32 v67, vcc, 0, v107, vcc
	global_load_dwordx2 v[74:75], v[66:67], off
	global_load_dwordx2 v[72:73], v[66:67], off offset:2048
	v_add_co_u32_e32 v66, vcc, 0x3000, v106
	v_lshlrev_b32_e32 v108, 16, v109
	s_nop 0
	v_addc_co_u32_e32 v67, vcc, 0, v107, vcc
	s_lshl_b32 vcc_lo, s17, 3
	s_or_b32 s85, vcc_lo, s9
	s_mulk_i32 s85, 0x410
	v_add_u32_e32 v102, s85, v101
	global_load_dwordx2 v[68:69], v[66:67], off
	s_nop 0
	global_load_dwordx2 v[66:67], v[66:67], off offset:2048
	ds_read_b128 v[102:105], v102
	v_readlane_b32 s17, v99, vcc_lo
	v_readlane_b32 s50, v100, vcc_lo
	v_and_b32_e32 v109, 0xffff0000, v109
	s_waitcnt lgkmcnt(0)
	v_fma_f32 v102, -v0, s17, v102
	v_fma_f32 v103, -v88, s17, v103
	v_fma_f32 v104, -v91, s17, v104
	v_fma_f32 v105, -v93, s17, v105
	v_fma_f32 v102, s50, v102, v87
	v_fma_f32 v103, s50, v103, v89
	v_fma_f32 v104, s50, v104, v92
	v_fma_f32 v105, s50, v105, v98
	v_mul_f32_e32 v102, 0xbfb8aa3b, v102
	v_mul_f32_e32 v103, 0xbfb8aa3b, v103
	v_mul_f32_e32 v104, 0xbfb8aa3b, v104
	v_mul_f32_e32 v105, 0xbfb8aa3b, v105
	v_exp_f32_e32 v102, v102
	v_exp_f32_e32 v103, v103
	v_exp_f32_e32 v104, v104
	v_exp_f32_e32 v105, v105
	v_add_f32_e32 v102, 1.0, v102
	v_add_f32_e32 v103, 1.0, v103
	v_add_f32_e32 v104, 1.0, v104
	v_add_f32_e32 v105, 1.0, v105
	v_rcp_f32_e32 v102, v102
	v_rcp_f32_e32 v103, v103
	v_rcp_f32_e32 v104, v104
	v_rcp_f32_e32 v105, v105
	s_or_b32 s50, vcc_lo, 1
	v_pk_mul_f32 v[102:103], v[102:103], v[110:111]
	s_or_b32 s63, s50, s9
	v_pk_mul_f32 v[104:105], v[104:105], v[108:109]
	v_cvt_pk_bf16_f32 v102, v102, v103
	v_cvt_pk_bf16_f32 v103, v104, v105
	s_mulk_i32 s63, 0x410
	global_store_dwordx2 v[106:107], v[102:103], off
	v_add_u32_e32 v102, s63, v101
	ds_read_b128 v[102:105], v102
	v_readlane_b32 s85, v99, s50
	v_readlane_b32 vcc_hi, v100, s50
	s_waitcnt vmcnt(7)
	v_lshlrev_b32_e32 v106, 16, v80
	v_and_b32_e32 v107, 0xffff0000, v80
	s_waitcnt lgkmcnt(0)
	v_fma_f32 v80, -v91, s85, v104
	v_fma_f32 v80, vcc_hi, v80, v92
	v_mul_f32_e32 v80, 0xbfb8aa3b, v80
	v_exp_f32_e32 v80, v80
	v_fma_f32 v102, -v0, s85, v102
	v_fma_f32 v103, -v88, s85, v103
	v_fma_f32 v102, vcc_hi, v102, v87
	v_add_f32_e32 v80, 1.0, v80
	v_rcp_f32_e32 v104, v80
	v_fma_f32 v80, -v93, s85, v105
	v_fma_f32 v103, vcc_hi, v103, v89
	v_fma_f32 v80, vcc_hi, v80, v98
	v_mul_f32_e32 v102, 0xbfb8aa3b, v102
	v_mul_f32_e32 v103, 0xbfb8aa3b, v103
	v_mul_f32_e32 v80, 0xbfb8aa3b, v80
	v_exp_f32_e32 v102, v102
	v_exp_f32_e32 v103, v103
	v_exp_f32_e32 v80, v80
	s_lshl_b32 s50, s50, 11
	v_add_f32_e32 v102, 1.0, v102
	v_add_f32_e32 v103, 1.0, v103
	v_add_f32_e32 v80, 1.0, v80
	v_rcp_f32_e32 v102, v102
	v_rcp_f32_e32 v103, v103
	v_rcp_f32_e32 v105, v80
	v_lshlrev_b32_e32 v80, 16, v81
	v_and_b32_e32 v81, 0xffff0000, v81
	v_pk_mul_f32 v[102:103], v[102:103], v[106:107]
	v_pk_mul_f32 v[80:81], v[104:105], v[80:81]
	v_cvt_pk_bf16_f32 v102, v102, v103
	v_cvt_pk_bf16_f32 v103, v80, v81
	v_lshl_add_u64 v[80:81], v[70:71], 0, s[50:51]
	s_or_b32 s50, vcc_lo, 2
	s_or_b32 vcc_hi, s50, s9
	s_mulk_i32 vcc_hi, 0x410
	global_store_dwordx2 v[80:81], v[102:103], off
	v_add_u32_e32 v80, vcc_hi, v101
	ds_read_b128 v[102:105], v80
	v_readlane_b32 s63, v99, s50
	v_readlane_b32 s85, v100, s50
	s_lshl_b32 s50, s50, 11
	s_mov_b32 s17, 1
	s_waitcnt lgkmcnt(0)
	v_fma_f32 v80, -v0, s63, v102
	v_fma_f32 v81, -v88, s63, v103
	v_fma_f32 v80, s85, v80, v87
	v_fma_f32 v81, s85, v81, v89
	v_mul_f32_e32 v80, 0xbfb8aa3b, v80
	v_mul_f32_e32 v81, 0xbfb8aa3b, v81
	v_exp_f32_e32 v80, v80
	v_exp_f32_e32 v81, v81
	s_waitcnt vmcnt(7)
	v_lshlrev_b32_e32 v102, 16, v78
	v_and_b32_e32 v103, 0xffff0000, v78
	v_fma_f32 v78, -v91, s63, v104
	v_fma_f32 v78, s85, v78, v92
	v_mul_f32_e32 v78, 0xbfb8aa3b, v78
	v_add_f32_e32 v80, 1.0, v80
	v_add_f32_e32 v81, 1.0, v81
	v_exp_f32_e32 v78, v78
	v_rcp_f32_e32 v80, v80
	v_rcp_f32_e32 v81, v81
	v_add_f32_e32 v78, 1.0, v78
	v_pk_mul_f32 v[80:81], v[80:81], v[102:103]
	v_rcp_f32_e32 v102, v78
	v_fma_f32 v78, -v93, s63, v105
	v_fma_f32 v78, s85, v78, v98
	v_mul_f32_e32 v78, 0xbfb8aa3b, v78
	v_exp_f32_e32 v78, v78
	v_cvt_pk_bf16_f32 v80, v80, v81
	v_add_f32_e32 v78, 1.0, v78
	v_rcp_f32_e32 v103, v78
	v_lshlrev_b32_e32 v78, 16, v79
	v_and_b32_e32 v79, 0xffff0000, v79
	v_pk_mul_f32 v[78:79], v[102:103], v[78:79]
	s_nop 0
	v_cvt_pk_bf16_f32 v81, v78, v79
	v_lshl_add_u64 v[78:79], v[70:71], 0, s[50:51]
	s_or_b32 s50, vcc_lo, 3
	s_or_b32 vcc_hi, s50, s9
	s_mulk_i32 vcc_hi, 0x410
	global_store_dwordx2 v[78:79], v[80:81], off
	v_add_u32_e32 v78, vcc_hi, v101
	ds_read_b128 v[78:81], v78
	v_readlane_b32 s63, v99, s50
	v_readlane_b32 s85, v100, s50
	s_waitcnt vmcnt(7)
	v_lshlrev_b32_e32 v102, 16, v76
	v_and_b32_e32 v103, 0xffff0000, v76
	s_waitcnt lgkmcnt(0)
; DI unsigned pack2(float a, float b) { fl2_t v = {a, b}; bf2_t r = __builtin_convertvector(v, bf2_t); return __builtin_bit_cast(unsigned, r); }
; DI float bflo(unsigned u) { return __uint_as_float(u << 16); }
; DI float bfhi(unsigned u) { return __uint_as_float(u & 0xffff0000u); }
; DI float sigmoidf_(float x) { return __builtin_amdgcn_rcpf(1.f + __builtin_amdgcn_exp2f(-1.4426950408889634f * x)); }
; DI float rl(float v, int srclane) { return __int_as_float(__builtin_amdgcn_readlane(__float_as_int(v), srclane)); }
; DI void epi_rows(const Params& p, int L, int ekind, const float* T, int rbase, int bcol) {
;     ...
;         for (int i = 0; i < 8; ++i) {
;           const int ri = ch * 8 + i;
;           const float mu = rl(rs_l.mu, ri), rstd = rl(rs_l.rstd, ri);
;           f32x4 t = *(const f32x4*)(T + (lr0 + ri) * TSTR + c4);
;           float sf[4] = {bflo(sv[i][0]), bfhi(sv[i][0]), bflo(sv[i][1]), bfhi(sv[i][1])};
;           float v[4];
;           for (int k = 0; k < 4; ++k) v[k] = sigmoidf_(rstd * (t[k] - mu * cs4[k]) + bw4[k]) * sf[k];
;           if (!a) { v[0] += bflo(mv[i][0]); v[1] += bfhi(mv[i][0]); v[2] += bflo(mv[i][1]); v[3] += bfhi(mv[i][1]); }
;           u32x2 o; o[0] = pack2(v[0], v[1]); o[1] = pack2(v[2], v[3]);
;           stg<u32x2>(Mx + (size_t)ri * 1024, o);
;         }
;       }
	v_fma_f32 v76, -v91, s63, v80
	v_fma_f32 v76, s85, v76, v92
	v_mul_f32_e32 v76, 0xbfb8aa3b, v76
	v_exp_f32_e32 v76, v76
	v_fma_f32 v78, -v0, s63, v78
	v_fma_f32 v79, -v88, s63, v79
	v_fma_f32 v78, s85, v78, v87
	v_add_f32_e32 v76, 1.0, v76
	v_rcp_f32_e32 v80, v76
	v_fma_f32 v76, -v93, s63, v81
	v_fma_f32 v79, s85, v79, v89
	v_fma_f32 v76, s85, v76, v98
	v_mul_f32_e32 v78, 0xbfb8aa3b, v78
	v_mul_f32_e32 v79, 0xbfb8aa3b, v79
	v_mul_f32_e32 v76, 0xbfb8aa3b, v76
	v_exp_f32_e32 v78, v78
	v_exp_f32_e32 v79, v79
	v_exp_f32_e32 v76, v76
	s_lshl_b32 s50, s50, 11
	v_add_f32_e32 v78, 1.0, v78
	v_add_f32_e32 v79, 1.0, v79
	v_add_f32_e32 v76, 1.0, v76
	v_rcp_f32_e32 v78, v78
	v_rcp_f32_e32 v79, v79
	v_rcp_f32_e32 v81, v76
	v_lshlrev_b32_e32 v76, 16, v77
	v_and_b32_e32 v77, 0xffff0000, v77
	v_pk_mul_f32 v[78:79], v[78:79], v[102:103]
	v_pk_mul_f32 v[76:77], v[80:81], v[76:77]
	v_cvt_pk_bf16_f32 v78, v78, v79
	v_cvt_pk_bf16_f32 v79, v76, v77
	v_lshl_add_u64 v[76:77], v[70:71], 0, s[50:51]
	s_or_b32 s50, vcc_lo, 4
	s_or_b32 vcc_hi, s50, s9
	s_mulk_i32 vcc_hi, 0x410
	global_store_dwordx2 v[76:77], v[78:79], off
	v_add_u32_e32 v76, vcc_hi, v101
	ds_read_b128 v[76:79], v76
	v_readlane_b32 s63, v99, s50
	v_readlane_b32 s85, v100, s50
	s_waitcnt vmcnt(7)
	v_lshlrev_b32_e32 v80, 16, v74
	v_and_b32_e32 v81, 0xffff0000, v74
	s_waitcnt lgkmcnt(0)
	v_fma_f32 v74, -v91, s63, v78
	v_fma_f32 v74, s85, v74, v92
	v_mul_f32_e32 v74, 0xbfb8aa3b, v74
	v_exp_f32_e32 v74, v74
	v_fma_f32 v76, -v0, s63, v76
	v_fma_f32 v77, -v88, s63, v77
	v_fma_f32 v76, s85, v76, v87
	v_add_f32_e32 v74, 1.0, v74
	v_rcp_f32_e32 v78, v74
	v_fma_f32 v74, -v93, s63, v79
	v_fma_f32 v77, s85, v77, v89
	v_fma_f32 v74, s85, v74, v98
	v_mul_f32_e32 v76, 0xbfb8aa3b, v76
	v_mul_f32_e32 v77, 0xbfb8aa3b, v77
	v_mul_f32_e32 v74, 0xbfb8aa3b, v74
	v_exp_f32_e32 v76, v76
	v_exp_f32_e32 v77, v77
	v_exp_f32_e32 v74, v74
	s_lshl_b32 s50, s50, 11
	v_add_f32_e32 v76, 1.0, v76
	v_add_f32_e32 v77, 1.0, v77
	v_add_f32_e32 v74, 1.0, v74
	v_rcp_f32_e32 v76, v76
	v_rcp_f32_e32 v77, v77
	v_rcp_f32_e32 v79, v74
	v_lshlrev_b32_e32 v74, 16, v75
	v_and_b32_e32 v75, 0xffff0000, v75
	v_pk_mul_f32 v[76:77], v[76:77], v[80:81]
	v_pk_mul_f32 v[74:75], v[78:79], v[74:75]
	v_cvt_pk_bf16_f32 v76, v76, v77
	v_cvt_pk_bf16_f32 v77, v74, v75
	v_lshl_add_u64 v[74:75], v[70:71], 0, s[50:51]
	s_or_b32 s50, vcc_lo, 5
	s_or_b32 vcc_hi, s50, s9
	s_mulk_i32 vcc_hi, 0x410
	global_store_dwordx2 v[74:75], v[76:77], off
	v_add_u32_e32 v74, vcc_hi, v101
	ds_read_b128 v[74:77], v74
	v_readlane_b32 s63, v99, s50
	v_readlane_b32 s85, v100, s50
	s_waitcnt vmcnt(7)
	v_lshlrev_b32_e32 v78, 16, v72
	v_and_b32_e32 v79, 0xffff0000, v72
	s_waitcnt lgkmcnt(0)
	v_fma_f32 v72, -v91, s63, v76
	v_fma_f32 v72, s85, v72, v92
	v_mul_f32_e32 v72, 0xbfb8aa3b, v72
	v_exp_f32_e32 v72, v72
	v_fma_f32 v74, -v0, s63, v74
	v_fma_f32 v75, -v88, s63, v75
	v_fma_f32 v74, s85, v74, v87
	v_add_f32_e32 v72, 1.0, v72
	v_rcp_f32_e32 v76, v72
	v_fma_f32 v72, -v93, s63, v77
	v_fma_f32 v75, s85, v75, v89
	v_fma_f32 v72, s85, v72, v98
	v_mul_f32_e32 v74, 0xbfb8aa3b, v74
	v_mul_f32_e32 v75, 0xbfb8aa3b, v75
	v_mul_f32_e32 v72, 0xbfb8aa3b, v72
	v_exp_f32_e32 v74, v74
	v_exp_f32_e32 v75, v75
	v_exp_f32_e32 v72, v72
	s_lshl_b32 s50, s50, 11
	v_add_f32_e32 v74, 1.0, v74
	v_add_f32_e32 v75, 1.0, v75
	v_add_f32_e32 v72, 1.0, v72
	v_rcp_f32_e32 v74, v74
	v_rcp_f32_e32 v75, v75
	v_rcp_f32_e32 v77, v72
	v_lshlrev_b32_e32 v72, 16, v73
	v_and_b32_e32 v73, 0xffff0000, v73
	v_pk_mul_f32 v[74:75], v[74:75], v[78:79]
	v_pk_mul_f32 v[72:73], v[76:77], v[72:73]
	v_cvt_pk_bf16_f32 v74, v74, v75
	v_cvt_pk_bf16_f32 v75, v72, v73
	v_lshl_add_u64 v[72:73], v[70:71], 0, s[50:51]
	s_or_b32 s50, vcc_lo, 6
	s_or_b32 vcc_hi, s50, s9
	s_mulk_i32 vcc_hi, 0x410
	global_store_dwordx2 v[72:73], v[74:75], off
	v_add_u32_e32 v72, vcc_hi, v101
	ds_read_b128 v[72:75], v72
	v_readlane_b32 s63, v99, s50
	v_readlane_b32 s85, v100, s50
	s_waitcnt vmcnt(7)
	v_lshlrev_b32_e32 v76, 16, v68
	v_and_b32_e32 v77, 0xffff0000, v68
	s_waitcnt lgkmcnt(0)
	v_fma_f32 v68, -v91, s63, v74
	v_fma_f32 v68, s85, v68, v92
	v_mul_f32_e32 v68, 0xbfb8aa3b, v68
	v_exp_f32_e32 v68, v68
	v_fma_f32 v72, -v0, s63, v72
	v_fma_f32 v73, -v88, s63, v73
	v_fma_f32 v72, s85, v72, v87
	v_add_f32_e32 v68, 1.0, v68
	v_rcp_f32_e32 v74, v68
	v_fma_f32 v68, -v93, s63, v75
	v_fma_f32 v73, s85, v73, v89
	v_fma_f32 v68, s85, v68, v98
	v_mul_f32_e32 v72, 0xbfb8aa3b, v72
	v_mul_f32_e32 v73, 0xbfb8aa3b, v73
	v_mul_f32_e32 v68, 0xbfb8aa3b, v68
	v_exp_f32_e32 v72, v72
	v_exp_f32_e32 v73, v73
	v_exp_f32_e32 v68, v68
	s_lshl_b32 s50, s50, 11
	v_add_f32_e32 v72, 1.0, v72
	v_add_f32_e32 v73, 1.0, v73
	v_add_f32_e32 v68, 1.0, v68
	v_rcp_f32_e32 v72, v72
	v_rcp_f32_e32 v73, v73
	v_rcp_f32_e32 v75, v68
	v_lshlrev_b32_e32 v68, 16, v69
	v_and_b32_e32 v69, 0xffff0000, v69
	v_pk_mul_f32 v[72:73], v[72:73], v[76:77]
	v_pk_mul_f32 v[68:69], v[74:75], v[68:69]
	v_cvt_pk_bf16_f32 v72, v72, v73
	v_cvt_pk_bf16_f32 v73, v68, v69
	v_lshl_add_u64 v[68:69], v[70:71], 0, s[50:51]
	s_or_b32 s50, vcc_lo, 7
	s_or_b32 vcc_lo, s50, s9
	s_mulk_i32 vcc_lo, 0x410
	global_store_dwordx2 v[68:69], v[72:73], off
	v_add_u32_e32 v68, vcc_lo, v101
	ds_read_b128 v[72:75], v68
	v_readlane_b32 s63, v99, s50
	v_readlane_b32 s85, v100, s50
	s_lshl_b32 s50, s50, 11
	s_and_b64 vcc, exec, s[68:69]
	s_waitcnt lgkmcnt(0)
	v_fma_f32 v68, -v0, s63, v72
	v_fma_f32 v69, -v88, s63, v73
	v_fma_f32 v68, s85, v68, v87
	v_fma_f32 v69, s85, v69, v89
	v_mul_f32_e32 v68, 0xbfb8aa3b, v68
	v_mul_f32_e32 v69, 0xbfb8aa3b, v69
	v_exp_f32_e32 v68, v68
	v_exp_f32_e32 v69, v69
	s_waitcnt vmcnt(7)
	v_lshlrev_b32_e32 v72, 16, v66
	v_and_b32_e32 v73, 0xffff0000, v66
	v_fma_f32 v66, -v91, s63, v74
	v_fma_f32 v66, s85, v66, v92
	v_mul_f32_e32 v66, 0xbfb8aa3b, v66
	v_add_f32_e32 v68, 1.0, v68
	v_add_f32_e32 v69, 1.0, v69
	v_exp_f32_e32 v66, v66
	v_rcp_f32_e32 v68, v68
	v_rcp_f32_e32 v69, v69
	s_mov_b64 s[68:69], 0
	v_add_f32_e32 v66, 1.0, v66
	v_pk_mul_f32 v[68:69], v[68:69], v[72:73]
	v_rcp_f32_e32 v72, v66
	v_fma_f32 v66, -v93, s63, v75
	v_fma_f32 v66, s85, v66, v98
	v_mul_f32_e32 v66, 0xbfb8aa3b, v66
	v_exp_f32_e32 v66, v66
	v_cvt_pk_bf16_f32 v68, v68, v69
	v_add_f32_e32 v66, 1.0, v66
	v_rcp_f32_e32 v73, v66
	v_lshlrev_b32_e32 v66, 16, v67
	v_and_b32_e32 v67, 0xffff0000, v67
	v_pk_mul_f32 v[66:67], v[72:73], v[66:67]
	s_nop 0
	v_cvt_pk_bf16_f32 v69, v66, v67
	v_lshl_add_u64 v[66:67], v[70:71], 0, s[50:51]
	global_store_dwordx2 v[66:67], v[68:69], off
	s_cbranch_vccnz .LBB0_1745
; DI void epi_dispatch(const Params& p, int L, int ekind, f32x4 (&acc)[2][2][4][2], int brow, int bcol, int, int, int, int) {
;     ...
;   for (int ai = 0; ai < 2; ++ai) {
;     __syncthreads();
;     #pragma unroll
;     for (int bj = 0; bj < 2; ++bj)
;       #pragma unroll
;       for (int m = 0; m < 4; ++m)
;         #pragma unroll
;         for (int n = 0; n < 2; ++n)
;           #pragma unroll
;           for (int j = 0; j < 4; ++j) tw[(m * 16 + j) * TSTR + bj * 128 + n * 16] = acc[ai][bj][m][n][j];
;     __syncthreads();
	v_readlane_b32 s68, v254, 25
	v_readlane_b32 s69, v254, 26
	v_readlane_b32 s70, v254, 27
	v_readlane_b32 s71, v254, 28
	s_mov_b64 s[68:69], s[70:71]
	v_mov_b32_e32 v0, v178
	s_barrier
	ds_write2_b32 v130, v2, v18 offset1:16
	ds_write2_b32 v114, v3, v19 offset0:4 offset1:20
	ds_write2_b32 v115, v4, v20 offset0:8 offset1:24
	ds_write2_b32 v116, v5, v21 offset0:12 offset1:28
	ds_write2_b32 v117, v6, v22 offset0:64 offset1:80
	ds_write2_b32 v82, v7, v23 offset0:68 offset1:84
	ds_write2_b32 v83, v8, v24 offset0:72 offset1:88
	ds_write2_b32 v84, v9, v25 offset0:76 offset1:92
	ds_write2_b32 v127, v10, v26 offset0:128 offset1:144
	ds_write2_b32 v85, v11, v27 offset0:132 offset1:148
	ds_write2_b32 v94, v12, v28 offset0:136 offset1:152
	ds_write2_b32 v95, v13, v29 offset0:140 offset1:156
	ds_write2_b32 v128, v14, v30 offset0:192 offset1:208
	ds_write2_b32 v96, v15, v31 offset0:196 offset1:212
	ds_write2_b32 v97, v16, v32 offset0:200 offset1:216
	ds_write2_b32 v126, v17, v33 offset0:204 offset1:220
	ds_write2_b32 v130, v34, v50 offset0:128 offset1:144
	ds_write2_b32 v114, v35, v51 offset0:132 offset1:148
	ds_write2_b32 v115, v36, v52 offset0:136 offset1:152
	ds_write2_b32 v116, v37, v53 offset0:140 offset1:156
	ds_write2_b32 v117, v38, v54 offset0:192 offset1:208
	ds_write2_b32 v82, v39, v55 offset0:196 offset1:212
	ds_write2_b32 v83, v40, v56 offset0:200 offset1:216
	ds_write2_b32 v84, v41, v57 offset0:204 offset1:220
	ds_write2_b32 v85, v42, v58 offset1:16
	ds_write2_b32 v94, v43, v59 offset0:4 offset1:20
	ds_write2_b32 v95, v44, v60 offset0:8 offset1:24
	ds_write2_b32 v90, v45, v61 offset0:12 offset1:28
	ds_write2_b32 v96, v46, v62 offset0:64 offset1:80
	ds_write2_b32 v97, v47, v63 offset0:68 offset1:84
	ds_write2_b32 v126, v48, v64 offset0:72 offset1:88
	ds_write2_b32 v86, v49, v65 offset0:76 offset1:92
	s_waitcnt lgkmcnt(0)
	s_barrier
; DI float fxc(const i64* p) { return (float)(*p) * FXC_INV; }
; DI RowStat row_stat(const i64* st, int row) {
;   float s = (float)st[2 * (size_t)row] * FXS_INV, q = (float)st[2 * (size_t)row + 1] * FXS_INV;
;   float mu = s * (1.f / 1024.f);
;   float var = fmaxf(q * (1.f / 1024.f) - mu * mu, 0.f);
;   RowStat r; r.mu = mu; r.rstd = rsqrtf(var + 1e-5f); return r;
; DI void epi_rows(const Params& p, int L, int ekind, const float* T, int rbase, int bcol) {
;     ...
;       const i64* st = ST_(L, 0); const int co = a ? CS_WGA : CS_WGB;
;       const size_t off0 = (size_t)(rbase + lr0) * 1024 + bcol + c4;
;       const u16* src = (const u16*)(R + (a ? R_MX : R_GT)) + off0; u16* Mx = (u16*)(R + R_MX) + off0;
;       f32x4 cs4, bw4;
;       for (int k = 0; k < 4; ++k) { cs4[k] = fxc(cs + co + bcol + c4 + k); bw4[k] = fxc(bw + co + bcol + c4 + k); }
;       RowStat rs_l = row_stat(st, myrow);
	s_add_u32 s17, s68, s12
	v_readfirstlane_b32 s9, v0
	s_addc_u32 s50, s69, s13
	s_ashr_i32 s9, s9, 2
	s_and_b32 s9, s9, -16
	v_lshlrev_b32_e32 v2, 2, v0
	v_and_b32_e32 v10, 0xfc, v2
	s_add_i32 vcc_lo, s9, s8
	v_and_or_b32 v2, v0, 15, vcc_lo
	v_lshlrev_b32_e32 v0, 1, v10
	s_ashr_i32 vcc_hi, vcc_lo, 31
	v_lshl_add_u64 v[4:5], s[68:69], 0, v[0:1]
	v_lshl_add_u64 v[4:5], s[6:7], 1, v[4:5]
	s_lshl_b64 vcc, vcc, 11
	v_lshl_add_u64 v[4:5], v[4:5], 0, vcc
	s_add_u32 vcc_lo, s17, s10
	v_lshlrev_b32_e32 v0, 3, v10
	s_addc_u32 vcc_hi, s50, s11
	v_lshl_add_u64 v[16:17], vcc, 0, v[0:1]
	s_mov_b32 s17, 0x39c000
	v_add_co_u32_e32 v12, vcc, s17, v16
	s_mov_b32 s50, 0x3d7000
	s_nop 0
	v_addc_co_u32_e32 v13, vcc, 0, v17, vcc
	flat_load_dwordx4 v[12:15], v[12:13] offset:2048
	s_mov_b64 s[70:71], 0xa0cda00
	v_lshl_add_u64 v[6:7], v[4:5], 0, s[70:71]
	s_mov_b64 s[70:71], 0x39c800
	v_lshl_add_u64 v[8:9], v[16:17], 0, s[70:71]
	s_mov_b64 s[70:71], 0x3d7800
	v_lshl_add_u64 v[4:5], v[16:17], 0, s[70:71]
	s_add_u32 s68, s68, s14
	s_addc_u32 s69, s69, s15
	s_mov_b32 s17, 0
	v_lshl_add_u32 v27, v10, 2, 0
	flat_load_dwordx4 v[22:25], v[4:5] offset:16
	v_add_co_u32_e32 v192, vcc, s50, v16
	s_nop 1
	v_addc_co_u32_e32 v193, vcc, 0, v17, vcc
	flat_load_dwordx4 v[188:191], v[192:193] offset:2048
	flat_load_dwordx4 v[196:199], v[8:9] offset:16
	v_mov_b32_e32 v208, v2
	v_ashrrev_i32_e32 v209, 31, v208
	v_lshl_add_u64 v[208:209], v[208:209], 4, s[68:69]
	flat_load_dwordx4 v[204:207], v[208:209]
	s_waitcnt vmcnt(0) lgkmcnt(0)
	v_xor_b32_e32 v0, v12, v13
	v_ashrrev_i32_e32 v0, 31, v0
	v_ffbh_i32_e32 v3, v13
	v_add_u32_e32 v0, 32, v0
	v_add_u32_e32 v3, -1, v3
	v_min_u32_e32 v0, v3, v0
	v_lshlrev_b64 v[12:13], v0, v[12:13]
	v_min_u32_e32 v3, 1, v12
	v_add_co_u32_e32 v12, vcc, s50, v16
	v_or_b32_e32 v3, v13, v3
	s_nop 0
	v_addc_co_u32_e32 v13, vcc, 0, v17, vcc
	v_mov_b64_e32 v[18:19], v[188:189]
	v_mov_b64_e32 v[20:21], v[190:191]
	v_cvt_f32_i32_e32 v3, v3
	v_sub_u32_e32 v0, 32, v0
	s_mov_b32 s50, 0x3a800000
	v_ffbh_i32_e32 v4, v23
	v_ldexp_f32 v0, v3, v0
	v_mul_f32_e32 v0, 0x2f800000, v0
	v_add_u32_e32 v4, -1, v4
	s_waitcnt vmcnt(0) lgkmcnt(0)
	v_xor_b32_e32 v3, v18, v19
	v_ashrrev_i32_e32 v3, 31, v3
	v_ffbh_i32_e32 v11, v19
	v_add_u32_e32 v3, 32, v3
	v_add_u32_e32 v11, -1, v11
	v_min_u32_e32 v3, v11, v3
	v_lshlrev_b64 v[12:13], v3, v[18:19]
	v_min_u32_e32 v11, 1, v12
	v_or_b32_e32 v11, v13, v11
	v_cvt_f32_i32_e32 v11, v11
	v_sub_u32_e32 v3, 32, v3
	v_ldexp_f32 v3, v11, v3
	v_mul_f32_e32 v18, 0x2f800000, v3
	v_xor_b32_e32 v3, v14, v15
	v_ashrrev_i32_e32 v3, 31, v3
	v_ffbh_i32_e32 v11, v15
	v_add_u32_e32 v3, 32, v3
	v_add_u32_e32 v11, -1, v11
	v_min_u32_e32 v3, v11, v3
	v_lshlrev_b64 v[12:13], v3, v[14:15]
	v_min_u32_e32 v11, 1, v12
	v_or_b32_e32 v11, v13, v11
	v_cvt_f32_i32_e32 v11, v11
	v_sub_u32_e32 v3, 32, v3
	v_ldexp_f32 v3, v11, v3
	v_mul_f32_e32 v19, 0x2f800000, v3
	v_xor_b32_e32 v3, v20, v21
	v_ashrrev_i32_e32 v3, 31, v3
	v_ffbh_i32_e32 v11, v21
	v_add_u32_e32 v3, 32, v3
	v_add_u32_e32 v11, -1, v11
	v_min_u32_e32 v3, v11, v3
	v_lshlrev_b64 v[12:13], v3, v[20:21]
	v_min_u32_e32 v11, 1, v12
	v_or_b32_e32 v11, v13, v11
	v_mov_b64_e32 v[12:13], v[196:197]
	v_mov_b64_e32 v[14:15], v[198:199]
	v_cvt_f32_i32_e32 v11, v11
	v_sub_u32_e32 v3, 32, v3
	v_ldexp_f32 v3, v11, v3
	v_mul_f32_e32 v20, 0x2f800000, v3
	s_waitcnt vmcnt(0) lgkmcnt(0)
	v_xor_b32_e32 v3, v12, v13
	v_ashrrev_i32_e32 v3, 31, v3
	v_ffbh_i32_e32 v8, v13
	v_add_u32_e32 v3, 32, v3
	v_add_u32_e32 v8, -1, v8
	v_min_u32_e32 v3, v8, v3
	v_lshlrev_b64 v[8:9], v3, v[12:13]
	v_min_u32_e32 v8, 1, v8
	v_or_b32_e32 v8, v9, v8
	v_cvt_f32_i32_e32 v8, v8
	v_sub_u32_e32 v3, 32, v3
	v_ldexp_f32 v3, v8, v3
	v_mul_f32_e32 v21, 0x2f800000, v3
	v_xor_b32_e32 v3, v22, v23
	v_ashrrev_i32_e32 v3, 31, v3
	v_add_u32_e32 v3, 32, v3
	v_min_u32_e32 v3, v4, v3
	v_lshlrev_b64 v[4:5], v3, v[22:23]
	v_min_u32_e32 v4, 1, v4
	v_or_b32_e32 v4, v5, v4
	v_cvt_f32_i32_e32 v4, v4
	v_sub_u32_e32 v3, 32, v3
	v_ldexp_f32 v3, v4, v3
	v_mul_f32_e32 v22, 0x2f800000, v3
	v_xor_b32_e32 v3, v14, v15
	v_ashrrev_i32_e32 v3, 31, v3
	v_ffbh_i32_e32 v4, v15
	v_add_u32_e32 v3, 32, v3
	v_add_u32_e32 v4, -1, v4
	v_min_u32_e32 v3, v4, v3
	v_lshlrev_b64 v[4:5], v3, v[14:15]
	v_min_u32_e32 v4, 1, v4
	v_or_b32_e32 v4, v5, v4
	v_cvt_f32_i32_e32 v4, v4
	v_sub_u32_e32 v3, 32, v3
	v_ldexp_f32 v3, v4, v3
	v_mul_f32_e32 v23, 0x2f800000, v3
	v_xor_b32_e32 v3, v24, v25
	v_ashrrev_i32_e32 v3, 31, v3
	v_ffbh_i32_e32 v4, v25
	v_add_u32_e32 v3, 32, v3
	v_add_u32_e32 v4, -1, v4
	v_min_u32_e32 v3, v4, v3
	v_lshlrev_b64 v[4:5], v3, v[24:25]
	v_min_u32_e32 v4, 1, v4
	v_or_b32_e32 v4, v5, v4
	v_cvt_f32_i32_e32 v4, v4
	v_sub_u32_e32 v3, 32, v3
	v_ldexp_f32 v3, v4, v3
	v_mul_f32_e32 v24, 0x2f800000, v3
	v_ashrrev_i32_e32 v3, 31, v2
	v_lshl_add_u64 v[2:3], v[2:3], 4, s[68:69]
	v_mov_b64_e32 v[2:3], v[204:205]
	v_mov_b64_e32 v[4:5], v[206:207]
	s_mov_b64 s[68:69], -1
	s_waitcnt vmcnt(0) lgkmcnt(0)
	v_xor_b32_e32 v8, v2, v3
	v_ashrrev_i32_e32 v8, 31, v8
	v_ffbh_i32_e32 v9, v3
	v_add_u32_e32 v8, 32, v8
	v_add_u32_e32 v9, -1, v9
	v_min_u32_e32 v8, v9, v8
	v_lshlrev_b64 v[2:3], v8, v[2:3]
	v_min_u32_e32 v2, 1, v2
	v_or_b32_e32 v2, v3, v2
	v_cvt_f32_i32_e32 v2, v2
	v_sub_u32_e32 v3, 32, v8
	v_ldexp_f32 v2, v2, v3
	v_mul_f32_e32 v8, 0x33800000, v2
	v_xor_b32_e32 v2, v4, v5
	v_ashrrev_i32_e32 v2, 31, v2
	v_ffbh_i32_e32 v3, v5
	v_add_u32_e32 v2, 32, v2
	v_add_u32_e32 v3, -1, v3
	v_min_u32_e32 v9, v3, v2
	v_lshlrev_b64 v[2:3], v9, v[4:5]
	v_min_u32_e32 v2, 1, v2
	v_or_b32_e32 v2, v3, v2
	v_cvt_f32_i32_e32 v2, v2
	v_sub_u32_e32 v3, 32, v9
	v_mul_f32_e32 v25, 0x3a800000, v8
	v_ldexp_f32 v2, v2, v3
	v_mul_f32_e32 v2, 0x33800000, v2
	v_mul_f32_e32 v3, v25, v25
	v_fma_f32 v2, v2, s50, -v3
	v_max_f32_e32 v2, 0, v2
	v_add_f32_e32 v2, 0x3727c5ac, v2
	s_mov_b32 s50, 0x800000
	v_cmp_gt_f32_e32 vcc, s50, v2
	v_mul_f32_e32 v3, 0x4b800000, v2
	s_nop 0
	v_cndmask_b32_e32 v2, v2, v3, vcc
	v_rsq_f32_e32 v2, v2
	s_nop 0
	v_mul_f32_e32 v3, 0x45800000, v2
	v_cndmask_b32_e32 v26, v2, v3, vcc

; DI float fxc(const i64* p) { return (float)(*p) * FXC_INV; }
; DI void epi_rows(const Params& p, int L, int ekind, const float* T, int rbase, int bcol) {
;     ...
;       const i64* st = ST_(L, 0); const int co = a ? CS_WGA : CS_WGB;
;       const size_t off0 = (size_t)(rbase + lr0) * 1024 + bcol + c4;
;       const u16* src = (const u16*)(R + (a ? R_MX : R_GT)) + off0; u16* Mx = (u16*)(R + R_MX) + off0;
;       f32x4 cs4, bw4;
;       for (int k = 0; k < 4; ++k) { cs4[k] = fxc(cs + co + bcol + c4 + k); bw4[k] = fxc(bw + co + bcol + c4 + k); }
;       RowStat rs_l = row_stat(st, myrow);
; DI void epi_dispatch(const Params& p, int L, int ekind, f32x4 (&acc)[2][2][4][2], int brow, int bcol, int, int, int, int) {
;     ...
;   for (int ai = 0; ai < 2; ++ai) {
;     __syncthreads();
;     #pragma unroll
;     for (int bj = 0; bj < 2; ++bj)
;       #pragma unroll
;       for (int m = 0; m < 4; ++m)
;         #pragma unroll
;         for (int n = 0; n < 2; ++n)
;           #pragma unroll
;           for (int j = 0; j < 4; ++j) tw[(m * 16 + j) * TSTR + bj * 128 + n * 16] = acc[ai][bj][m][n][j];
;     __syncthreads();
.LBB0_1764:
	s_or_b64 exec, exec, s[4:5]
	v_mov_b32_e32 v0, v178
	s_movk_i32 s4, 0x410
	v_lshrrev_b32_e32 v131, 2, v0
	v_and_b32_e32 v131, 0xfffffcc, v131
	v_and_b32_e32 v130, 15, v0
	v_mul_lo_u32 v131, v131, s4
	v_lshlrev_b32_e32 v0, 1, v0
	v_add_u32_e32 v131, 0, v131
	v_and_b32_e32 v0, 0x180, v0
	v_lshlrev_b32_e32 v130, 2, v130
	v_add3_u32 v130, v131, v0, v130
	s_waitcnt vmcnt(0)
	s_barrier
	ds_write2_b32 v130, v114, v126 offset1:16
	v_add_u32_e32 v114, 0x400, v130
	ds_write2_b32 v114, v115, v127 offset0:4 offset1:20
	v_add_u32_e32 v115, 0x800, v130
	ds_write2_b32 v115, v116, v128 offset0:8 offset1:24
	v_add_u32_e32 v116, 0xc00, v130
	v_readlane_b32 s24, v254, 25
	ds_write2_b32 v116, v117, v129 offset0:12 offset1:28
	v_add_u32_e32 v117, 0x4000, v130
	v_add_u32_e32 v126, 0x4400, v130
	v_add_u32_e32 v127, 0x4800, v130
	v_add_u32_e32 v128, 0x4c00, v130
	v_add_u32_e32 v136, 0x8000, v130
	v_add_u32_e32 v129, 0x8400, v130
	v_add_u32_e32 v131, 0x8800, v130
	v_add_u32_e32 v132, 0x8c00, v130
	v_add_u32_e32 v137, 0xc000, v130
	v_add_u32_e32 v133, 0xc400, v130
	v_add_u32_e32 v134, 0xc800, v130
	v_add_u32_e32 v135, 0xcc00, v130
	v_readlane_b32 s26, v254, 27
	v_readlane_b32 s27, v254, 28
	ds_write2_b32 v117, v82, v94 offset0:64 offset1:80
	ds_write2_b32 v126, v83, v95 offset0:68 offset1:84
	ds_write2_b32 v127, v84, v96 offset0:72 offset1:88
	ds_write2_b32 v128, v85, v97 offset0:76 offset1:92
	ds_write2_b32 v136, v74, v78 offset0:128 offset1:144
	ds_write2_b32 v129, v75, v79 offset0:132 offset1:148
	ds_write2_b32 v131, v76, v80 offset0:136 offset1:152
	ds_write2_b32 v132, v77, v81 offset0:140 offset1:156
	ds_write2_b32 v137, v66, v70 offset0:192 offset1:208
	ds_write2_b32 v133, v67, v71 offset0:196 offset1:212
	ds_write2_b32 v134, v68, v72 offset0:200 offset1:216
	ds_write2_b32 v135, v69, v73 offset0:204 offset1:220
	ds_write2_b32 v130, v98, v118 offset0:128 offset1:144
	ds_write2_b32 v114, v99, v119 offset0:132 offset1:148
	ds_write2_b32 v115, v100, v120 offset0:136 offset1:152
	ds_write2_b32 v116, v101, v121 offset0:140 offset1:156
	ds_write2_b32 v117, v102, v122 offset0:192 offset1:208
	ds_write2_b32 v126, v103, v123 offset0:196 offset1:212
	ds_write2_b32 v127, v104, v124 offset0:200 offset1:216
	ds_write2_b32 v128, v105, v125 offset0:204 offset1:220
	ds_write2_b32 v129, v90, v110 offset1:16
	ds_write2_b32 v131, v91, v111 offset0:4 offset1:20
	ds_write2_b32 v132, v92, v112 offset0:8 offset1:24
	v_add_u32_e32 v98, 0x9000, v130
	v_add_u32_e32 v99, 0xd000, v130
	s_mov_b64 s[4:5], s[26:27]
	v_mov_b32_e32 v0, v178
	ds_write2_b32 v98, v93, v113 offset0:12 offset1:28
	ds_write2_b32 v133, v86, v106 offset0:64 offset1:80
	ds_write2_b32 v134, v87, v107 offset0:68 offset1:84
	ds_write2_b32 v135, v88, v108 offset0:72 offset1:88
	ds_write2_b32 v99, v89, v109 offset0:76 offset1:92
	s_waitcnt lgkmcnt(0)
	s_barrier
	s_add_u32 s18, s4, s12
	v_readfirstlane_b32 s9, v0
	s_addc_u32 s19, s5, s13
	s_ashr_i32 s9, s9, 2
	s_and_b32 s9, s9, -16
	v_lshlrev_b32_e32 v66, 2, v0
	s_add_i32 s16, s9, s16
	v_and_b32_e32 v76, 0xfc, v66
	s_ashr_i32 s17, s16, 31
	v_and_or_b32 v66, v0, 15, s16
	s_lshl_b64 s[16:17], s[16:17], 10
	v_or_b32_e32 v68, s6, v76
	v_mov_b32_e32 v69, s7
	v_lshl_add_u64 v[68:69], s[16:17], 0, v[68:69]
	v_lshl_add_u64 v[68:69], v[68:69], 1, s[4:5]
	s_mov_b64 s[16:17], 0xe1cda00
	v_lshl_add_u64 v[70:71], v[68:69], 0, s[16:17]
	s_add_u32 s16, s18, s10
	v_lshlrev_b32_e32 v0, 3, v76
	s_addc_u32 s17, s19, s11
	v_lshl_add_u64 v[82:83], s[16:17], 0, v[0:1]
	s_mov_b64 s[16:17], 0x39e800
	v_lshl_add_u64 v[74:75], v[82:83], 0, s[16:17]
	s_mov_b64 s[16:17], 0x3d9800
	v_lshl_add_u64 v[72:73], v[82:83], 0, s[16:17]
	s_mov_b32 s16, 0x39e000
	v_add_co_u32_e32 v78, vcc, s16, v82
	s_mov_b32 s17, 0x3d9000
	s_nop 0
	v_addc_co_u32_e32 v79, vcc, 0, v83, vcc
	flat_load_dwordx4 v[78:81], v[78:79] offset:2048
	s_add_u32 s4, s4, s14
	s_addc_u32 s5, s5, s15
	s_mov_b64 s[18:19], 0xa0cda00
	s_mov_b32 s16, 0
	v_lshl_add_u32 v109, v76, 2, 0
	v_readlane_b32 s25, v254, 26
	v_add_co_u32_e32 v192, vcc, s17, v82
	s_nop 1
	v_addc_co_u32_e32 v193, vcc, 0, v83, vcc
	flat_load_dwordx4 v[188:191], v[192:193] offset:2048
	flat_load_dwordx4 v[196:199], v[74:75] offset:16
	flat_load_dwordx4 v[204:207], v[72:73] offset:16
	v_mov_b32_e32 v216, v66
	v_ashrrev_i32_e32 v217, 31, v216
	v_lshl_add_u64 v[216:217], v[216:217], 4, s[4:5]
	flat_load_dwordx4 v[212:215], v[216:217]
	s_waitcnt vmcnt(0) lgkmcnt(0)
	v_xor_b32_e32 v0, v78, v79
	v_ashrrev_i32_e32 v0, 31, v0
	v_ffbh_i32_e32 v67, v79
	v_add_u32_e32 v0, 32, v0
	v_add_u32_e32 v67, -1, v67
	v_min_u32_e32 v0, v67, v0
	v_lshlrev_b64 v[78:79], v0, v[78:79]
	v_min_u32_e32 v67, 1, v78
	v_add_co_u32_e32 v78, vcc, s17, v82
	v_or_b32_e32 v67, v79, v67
	s_nop 0
	v_addc_co_u32_e32 v79, vcc, 0, v83, vcc
	v_mov_b64_e32 v[82:83], v[188:189]
	v_mov_b64_e32 v[84:85], v[190:191]
	v_cvt_f32_i32_e32 v67, v67
	v_sub_u32_e32 v0, 32, v0
	v_ldexp_f32 v0, v67, v0
	v_mul_f32_e32 v0, 0x2f800000, v0
	s_waitcnt vmcnt(0) lgkmcnt(0)
	v_xor_b32_e32 v67, v82, v83
	v_ashrrev_i32_e32 v67, 31, v67
	v_ffbh_i32_e32 v77, v83
	v_add_u32_e32 v67, 32, v67
	v_add_u32_e32 v77, -1, v77
	v_min_u32_e32 v67, v77, v67
	v_lshlrev_b64 v[78:79], v67, v[82:83]
	v_min_u32_e32 v77, 1, v78
	v_or_b32_e32 v77, v79, v77
	v_cvt_f32_i32_e32 v77, v77
	v_sub_u32_e32 v67, 32, v67
	v_ldexp_f32 v67, v77, v67
	v_mul_f32_e32 v100, 0x2f800000, v67
	v_xor_b32_e32 v67, v80, v81
	v_ashrrev_i32_e32 v67, 31, v67
	v_ffbh_i32_e32 v77, v81
	v_add_u32_e32 v67, 32, v67
	v_add_u32_e32 v77, -1, v77
	v_min_u32_e32 v67, v77, v67
	v_lshlrev_b64 v[78:79], v67, v[80:81]
	v_min_u32_e32 v77, 1, v78
	v_or_b32_e32 v77, v79, v77
	v_cvt_f32_i32_e32 v77, v77
	v_sub_u32_e32 v67, 32, v67
	v_ldexp_f32 v67, v77, v67
	v_mul_f32_e32 v101, 0x2f800000, v67
	v_xor_b32_e32 v67, v84, v85
	v_ashrrev_i32_e32 v67, 31, v67
	v_ffbh_i32_e32 v77, v85
	v_add_u32_e32 v67, 32, v67
	v_add_u32_e32 v77, -1, v77
	v_min_u32_e32 v67, v77, v67
	v_lshlrev_b64 v[78:79], v67, v[84:85]
	v_min_u32_e32 v77, 1, v78
	v_or_b32_e32 v77, v79, v77
	v_mov_b64_e32 v[78:79], v[196:197]
	v_mov_b64_e32 v[80:81], v[198:199]
	v_cvt_f32_i32_e32 v77, v77
	v_sub_u32_e32 v67, 32, v67
	v_ldexp_f32 v67, v77, v67
	v_mul_f32_e32 v102, 0x2f800000, v67
	s_waitcnt vmcnt(0) lgkmcnt(0)
; DI unsigned pack2(float a, float b) { fl2_t v = {a, b}; bf2_t r = __builtin_convertvector(v, bf2_t); return __builtin_bit_cast(unsigned, r); }
; DI float bflo(unsigned u) { return __uint_as_float(u << 16); }
; DI float bfhi(unsigned u) { return __uint_as_float(u & 0xffff0000u); }
; DI float sigmoidf_(float x) { return __builtin_amdgcn_rcpf(1.f + __builtin_amdgcn_exp2f(-1.4426950408889634f * x)); }
; DI float fxc(const i64* p) { return (float)(*p) * FXC_INV; }
; DI float rl(float v, int srclane) { return __int_as_float(__builtin_amdgcn_readlane(__float_as_int(v), srclane)); }
; DI RowStat row_stat(const i64* st, int row) {
;   float s = (float)st[2 * (size_t)row] * FXS_INV, q = (float)st[2 * (size_t)row + 1] * FXS_INV;
;   float mu = s * (1.f / 1024.f);
;   float var = fmaxf(q * (1.f / 1024.f) - mu * mu, 0.f);
;   RowStat r; r.mu = mu; r.rstd = rsqrtf(var + 1e-5f); return r;
; DI void epi_rows(const Params& p, int L, int ekind, const float* T, int rbase, int bcol) {
;     ...
;       for (int k = 0; k < 4; ++k) { cs4[k] = fxc(cs + co + bcol + c4 + k); bw4[k] = fxc(bw + co + bcol + c4 + k); }
;       RowStat rs_l = row_stat(st, myrow);
;       #pragma unroll 1
;       for (int ch = 0; ch < 2; ++ch) {
;         u32x2 sv[8], mv[8];
;         #pragma unroll
;         for (int i = 0; i < 8; ++i) {
;           sv[i] = ldg<u32x2>(src + (size_t)(ch * 8 + i) * 1024);
;           if (!a) mv[i] = ldg<u32x2>(Mx + (size_t)(ch * 8 + i) * 1024);
;         }
;         #pragma unroll
;         for (int i = 0; i < 8; ++i) {
;           const int ri = ch * 8 + i;
;           const float mu = rl(rs_l.mu, ri), rstd = rl(rs_l.rstd, ri);
;           f32x4 t = *(const f32x4*)(T + (lr0 + ri) * TSTR + c4);
;           float sf[4] = {bflo(sv[i][0]), bfhi(sv[i][0]), bflo(sv[i][1]), bfhi(sv[i][1])};
;           float v[4];
;           for (int k = 0; k < 4; ++k) v[k] = sigmoidf_(rstd * (t[k] - mu * cs4[k]) + bw4[k]) * sf[k];
;           if (!a) { v[0] += bflo(mv[i][0]); v[1] += bfhi(mv[i][0]); v[2] += bflo(mv[i][1]); v[3] += bfhi(mv[i][1]); }
;           u32x2 o; o[0] = pack2(v[0], v[1]); o[1] = pack2(v[2], v[3]);
;           stg<u32x2>(Mx + (size_t)ri * 1024, o);
;         }
	v_xor_b32_e32 v67, v78, v79
	v_ashrrev_i32_e32 v67, 31, v67
	v_ffbh_i32_e32 v74, v79
	v_add_u32_e32 v67, 32, v67
	v_add_u32_e32 v74, -1, v74
	v_min_u32_e32 v67, v74, v67
	v_lshlrev_b64 v[74:75], v67, v[78:79]
	v_min_u32_e32 v74, 1, v74
	v_or_b32_e32 v74, v75, v74
	v_cvt_f32_i32_e32 v74, v74
	v_sub_u32_e32 v67, 32, v67
	v_ldexp_f32 v67, v74, v67
	v_mov_b64_e32 v[72:73], v[204:205]
	v_mov_b64_e32 v[74:75], v[206:207]
	v_mul_f32_e32 v103, 0x2f800000, v67
	s_waitcnt vmcnt(0) lgkmcnt(0)
	v_xor_b32_e32 v67, v72, v73
	v_ashrrev_i32_e32 v67, 31, v67
	v_ffbh_i32_e32 v77, v73
	v_add_u32_e32 v67, 32, v67
	v_add_u32_e32 v77, -1, v77
	v_min_u32_e32 v67, v77, v67
	v_lshlrev_b64 v[72:73], v67, v[72:73]
	v_min_u32_e32 v72, 1, v72
	v_or_b32_e32 v72, v73, v72
	v_cvt_f32_i32_e32 v72, v72
	v_sub_u32_e32 v67, 32, v67
	v_ldexp_f32 v67, v72, v67
	v_mul_f32_e32 v104, 0x2f800000, v67
	v_xor_b32_e32 v67, v80, v81
	v_ashrrev_i32_e32 v67, 31, v67
	v_ffbh_i32_e32 v72, v81
	v_add_u32_e32 v67, 32, v67
	v_add_u32_e32 v72, -1, v72
	v_min_u32_e32 v67, v72, v67
	v_lshlrev_b64 v[72:73], v67, v[80:81]
	v_min_u32_e32 v72, 1, v72
	v_or_b32_e32 v72, v73, v72
	v_cvt_f32_i32_e32 v72, v72
	v_sub_u32_e32 v67, 32, v67
	v_ldexp_f32 v67, v72, v67
	v_mul_f32_e32 v105, 0x2f800000, v67
	v_xor_b32_e32 v67, v74, v75
	v_ashrrev_i32_e32 v67, 31, v67
	v_ffbh_i32_e32 v72, v75
	v_add_u32_e32 v67, 32, v67
	v_add_u32_e32 v72, -1, v72
	v_min_u32_e32 v67, v72, v67
	v_lshlrev_b64 v[72:73], v67, v[74:75]
	v_min_u32_e32 v72, 1, v72
	v_or_b32_e32 v72, v73, v72
	v_cvt_f32_i32_e32 v72, v72
	v_sub_u32_e32 v67, 32, v67
	v_ldexp_f32 v67, v72, v67
	v_mul_f32_e32 v106, 0x2f800000, v67
	v_ashrrev_i32_e32 v67, 31, v66
	v_lshl_add_u64 v[66:67], v[66:67], 4, s[4:5]
	v_lshl_add_u64 v[72:73], v[68:69], 0, s[18:19]
	v_mov_b64_e32 v[66:67], v[212:213]
	v_mov_b64_e32 v[68:69], v[214:215]
	s_mov_b32 s4, 0x3a800000
	s_waitcnt vmcnt(0) lgkmcnt(0)
	v_xor_b32_e32 v74, v66, v67
	v_ashrrev_i32_e32 v74, 31, v74
	v_ffbh_i32_e32 v75, v67
	v_add_u32_e32 v74, 32, v74
	v_add_u32_e32 v75, -1, v75
	v_min_u32_e32 v74, v75, v74
	v_lshlrev_b64 v[66:67], v74, v[66:67]
	v_min_u32_e32 v66, 1, v66
	v_or_b32_e32 v66, v67, v66
	v_cvt_f32_i32_e32 v66, v66
	v_sub_u32_e32 v67, 32, v74
	v_ldexp_f32 v66, v66, v67
	v_mul_f32_e32 v74, 0x33800000, v66
	v_xor_b32_e32 v66, v68, v69
	v_ashrrev_i32_e32 v66, 31, v66
	v_ffbh_i32_e32 v67, v69
	v_add_u32_e32 v66, 32, v66
	v_add_u32_e32 v67, -1, v67
	v_min_u32_e32 v75, v67, v66
	v_lshlrev_b64 v[66:67], v75, v[68:69]
	v_min_u32_e32 v66, 1, v66
	v_or_b32_e32 v66, v67, v66
	v_cvt_f32_i32_e32 v66, v66
	v_sub_u32_e32 v67, 32, v75
	v_mul_f32_e32 v107, 0x3a800000, v74
	v_ldexp_f32 v66, v66, v67
	v_mul_f32_e32 v66, 0x33800000, v66
	v_mul_f32_e32 v67, v107, v107
	v_fma_f32 v66, v66, s4, -v67
	v_max_f32_e32 v66, 0, v66
	v_add_f32_e32 v66, 0x3727c5ac, v66
	s_mov_b32 s4, 0x800000
	v_cmp_gt_f32_e32 vcc, s4, v66
	v_mul_f32_e32 v67, 0x4b800000, v66
	s_mov_b64 s[4:5], -1
	v_cndmask_b32_e32 v66, v66, v67, vcc
	v_rsq_f32_e32 v66, v66
	s_nop 0
	v_mul_f32_e32 v67, 0x45800000, v66
	v_cndmask_b32_e32 v108, v66, v67, vcc
.LBB0_1765:
	s_lshl_b32 s50, s16, 14
	v_lshl_add_u64 v[66:67], v[70:71], 0, s[50:51]
	global_load_dwordx2 v[118:119], v[66:67], off
	v_lshl_add_u64 v[120:121], v[72:73], 0, s[50:51]
	global_load_dwordx2 v[122:123], v[120:121], off
	global_load_dwordx2 v[96:97], v[66:67], off offset:2048
	global_load_dwordx2 v[94:95], v[120:121], off offset:2048
	s_or_b32 s18, s50, 0x1000
	s_mov_b32 s19, s51
	v_lshl_add_u64 v[66:67], v[70:71], 0, s[18:19]
	global_load_dwordx2 v[90:91], v[66:67], off
	v_lshl_add_u64 v[66:67], v[72:73], 0, s[18:19]
	global_load_dwordx2 v[92:93], v[66:67], off
	s_or_b32 s18, s50, 0x1800
	v_lshl_add_u64 v[66:67], v[70:71], 0, s[18:19]
	global_load_dwordx2 v[86:87], v[66:67], off
	v_lshl_add_u64 v[66:67], v[72:73], 0, s[18:19]
	s_or_b32 s18, s50, 0x2000
	global_load_dwordx2 v[88:89], v[66:67], off
	v_lshl_add_u64 v[66:67], v[70:71], 0, s[18:19]
	global_load_dwordx2 v[82:83], v[66:67], off
	v_lshl_add_u64 v[66:67], v[72:73], 0, s[18:19]
	s_or_b32 s18, s50, 0x2800
	global_load_dwordx2 v[84:85], v[66:67], off
	v_lshl_add_u64 v[66:67], v[70:71], 0, s[18:19]
	global_load_dwordx2 v[78:79], v[66:67], off
	v_lshl_add_u64 v[66:67], v[72:73], 0, s[18:19]
	s_or_b32 s18, s50, 0x3000
	global_load_dwordx2 v[80:81], v[66:67], off
	v_lshl_add_u64 v[66:67], v[70:71], 0, s[18:19]
	s_lshl_b32 s17, s16, 3
	global_load_dwordx2 v[74:75], v[66:67], off
	v_lshl_add_u64 v[66:67], v[72:73], 0, s[18:19]
	s_or_b32 s19, s17, s9
	s_mulk_i32 s19, 0x410
	v_add_u32_e32 v110, s19, v109
	ds_read_b128 v[110:113], v110
	v_readlane_b32 s16, v107, s17
	v_readlane_b32 s18, v108, s17
	s_or_b32 s50, s50, 0x3800
	global_load_dwordx2 v[76:77], v[66:67], off
	s_waitcnt lgkmcnt(0)
	v_fma_f32 v110, -v0, s16, v110
	v_fma_f32 v111, -v101, s16, v111
	v_fma_f32 v112, -v103, s16, v112
	v_fma_f32 v113, -v105, s16, v113
	v_fma_f32 v110, s18, v110, v100
	v_fma_f32 v111, s18, v111, v102
	v_fma_f32 v112, s18, v112, v104
	v_fma_f32 v113, s18, v113, v106
	v_mul_f32_e32 v110, 0xbfb8aa3b, v110
	v_mul_f32_e32 v111, 0xbfb8aa3b, v111
	v_mul_f32_e32 v112, 0xbfb8aa3b, v112
	v_mul_f32_e32 v113, 0xbfb8aa3b, v113
	v_exp_f32_e32 v110, v110
	v_exp_f32_e32 v111, v111
	v_exp_f32_e32 v112, v112
	v_exp_f32_e32 v113, v113
	v_add_f32_e32 v110, 1.0, v110
	v_add_f32_e32 v111, 1.0, v111
	v_add_f32_e32 v112, 1.0, v112
	v_add_f32_e32 v113, 1.0, v113
	v_rcp_f32_e32 v110, v110
	v_rcp_f32_e32 v111, v111
	v_rcp_f32_e32 v112, v112
	v_rcp_f32_e32 v113, v113
	s_or_b32 s18, s17, 1
	s_or_b32 s25, s18, s9
	v_lshl_add_u64 v[66:67], v[70:71], 0, s[50:51]
	v_lshl_add_u64 v[68:69], v[72:73], 0, s[50:51]
	s_mulk_i32 s25, 0x410
	global_load_dwordx2 v[66:67], v[66:67], off
	v_readlane_b32 s19, v107, s18
	global_load_dwordx2 v[68:69], v[68:69], off
	v_readlane_b32 s24, v108, s18
	s_lshl_b32 s50, s18, 11
	s_or_b32 s18, s17, 2
	s_mov_b32 s16, 1
	s_and_b64 vcc, exec, s[4:5]
	s_mov_b64 s[4:5], 0
	s_waitcnt vmcnt(14)
; DI unsigned pack2(float a, float b) { fl2_t v = {a, b}; bf2_t r = __builtin_convertvector(v, bf2_t); return __builtin_bit_cast(unsigned, r); }
; DI float bflo(unsigned u) { return __uint_as_float(u << 16); }
; DI float bfhi(unsigned u) { return __uint_as_float(u & 0xffff0000u); }
; DI float sigmoidf_(float x) { return __builtin_amdgcn_rcpf(1.f + __builtin_amdgcn_exp2f(-1.4426950408889634f * x)); }
; DI float rl(float v, int srclane) { return __int_as_float(__builtin_amdgcn_readlane(__float_as_int(v), srclane)); }
; DI void epi_rows(const Params& p, int L, int ekind, const float* T, int rbase, int bcol) {
;     ...
;         for (int i = 0; i < 8; ++i) {
;           const int ri = ch * 8 + i;
;           const float mu = rl(rs_l.mu, ri), rstd = rl(rs_l.rstd, ri);
;           f32x4 t = *(const f32x4*)(T + (lr0 + ri) * TSTR + c4);
;           float sf[4] = {bflo(sv[i][0]), bfhi(sv[i][0]), bflo(sv[i][1]), bfhi(sv[i][1])};
;           float v[4];
;           for (int k = 0; k < 4; ++k) v[k] = sigmoidf_(rstd * (t[k] - mu * cs4[k]) + bw4[k]) * sf[k];
;           if (!a) { v[0] += bflo(mv[i][0]); v[1] += bfhi(mv[i][0]); v[2] += bflo(mv[i][1]); v[3] += bfhi(mv[i][1]); }
;           u32x2 o; o[0] = pack2(v[0], v[1]); o[1] = pack2(v[2], v[3]);
;           stg<u32x2>(Mx + (size_t)ri * 1024, o);
;         }
	v_lshlrev_b32_e32 v138, 16, v122
	v_lshlrev_b32_e32 v124, 16, v118
	v_and_b32_e32 v125, 0xffff0000, v118
	v_and_b32_e32 v139, 0xffff0000, v122
	v_lshlrev_b32_e32 v118, 16, v119
	v_and_b32_e32 v119, 0xffff0000, v119
	v_lshlrev_b32_e32 v122, 16, v123
	v_and_b32_e32 v123, 0xffff0000, v123
	v_pk_fma_f32 v[110:111], v[110:111], v[124:125], v[138:139]
	v_pk_fma_f32 v[112:113], v[112:113], v[118:119], v[122:123]
	v_cvt_pk_bf16_f32 v110, v110, v111
	v_cvt_pk_bf16_f32 v111, v112, v113
	global_store_dwordx2 v[120:121], v[110:111], off
	v_add_u32_e32 v110, s25, v109
	ds_read_b128 v[110:113], v110
	s_waitcnt vmcnt(14)
	v_lshlrev_b32_e32 v118, 16, v96
	v_and_b32_e32 v119, 0xffff0000, v96
	s_waitcnt vmcnt(13)
	v_lshlrev_b32_e32 v120, 16, v94
	v_and_b32_e32 v121, 0xffff0000, v94
	s_waitcnt lgkmcnt(0)
	v_fma_f32 v110, -v0, s19, v110
	v_fma_f32 v111, -v101, s19, v111
	v_fma_f32 v112, -v103, s19, v112
	v_fma_f32 v113, -v105, s19, v113
	v_fma_f32 v110, s24, v110, v100
	v_fma_f32 v111, s24, v111, v102
	v_fma_f32 v112, s24, v112, v104
	v_fma_f32 v113, s24, v113, v106
	v_mul_f32_e32 v110, 0xbfb8aa3b, v110
	v_mul_f32_e32 v111, 0xbfb8aa3b, v111
	v_mul_f32_e32 v112, 0xbfb8aa3b, v112
	v_mul_f32_e32 v113, 0xbfb8aa3b, v113
	v_exp_f32_e32 v110, v110
	v_exp_f32_e32 v111, v111
	v_exp_f32_e32 v112, v112
	v_exp_f32_e32 v113, v113
	v_add_f32_e32 v110, 1.0, v110
	v_add_f32_e32 v111, 1.0, v111
	v_add_f32_e32 v112, 1.0, v112
	v_add_f32_e32 v113, 1.0, v113
	v_rcp_f32_e32 v110, v110
	v_rcp_f32_e32 v111, v111
	v_rcp_f32_e32 v112, v112
	v_rcp_f32_e32 v113, v113
	v_lshlrev_b32_e32 v96, 16, v97
	v_and_b32_e32 v97, 0xffff0000, v97
	v_lshlrev_b32_e32 v94, 16, v95
	v_and_b32_e32 v95, 0xffff0000, v95
	v_pk_fma_f32 v[110:111], v[110:111], v[118:119], v[120:121]
	v_pk_fma_f32 v[94:95], v[112:113], v[96:97], v[94:95]
	s_or_b32 s25, s18, s9
	v_cvt_pk_bf16_f32 v96, v110, v111
	v_cvt_pk_bf16_f32 v97, v94, v95
	v_lshl_add_u64 v[94:95], v[72:73], 0, s[50:51]
	s_mulk_i32 s25, 0x410
	global_store_dwordx2 v[94:95], v[96:97], off
	v_add_u32_e32 v94, s25, v109
	ds_read_b128 v[94:97], v94
	v_readlane_b32 s19, v107, s18
	v_readlane_b32 s24, v108, s18
	s_waitcnt vmcnt(13)
	v_lshlrev_b32_e32 v110, 16, v90
	v_and_b32_e32 v111, 0xffff0000, v90
	s_waitcnt lgkmcnt(0)
	v_fma_f32 v94, -v0, s19, v94
	v_fma_f32 v95, -v101, s19, v95
	v_fma_f32 v96, -v103, s19, v96
	v_fma_f32 v97, -v105, s19, v97
	v_fma_f32 v94, s24, v94, v100
	v_fma_f32 v95, s24, v95, v102
	v_fma_f32 v96, s24, v96, v104
	v_fma_f32 v97, s24, v97, v106
	v_mul_f32_e32 v94, 0xbfb8aa3b, v94
	v_mul_f32_e32 v95, 0xbfb8aa3b, v95
	v_mul_f32_e32 v96, 0xbfb8aa3b, v96
	v_mul_f32_e32 v97, 0xbfb8aa3b, v97
	v_exp_f32_e32 v94, v94
	v_exp_f32_e32 v95, v95
	v_exp_f32_e32 v96, v96
	v_exp_f32_e32 v97, v97
	v_add_f32_e32 v94, 1.0, v94
	v_add_f32_e32 v95, 1.0, v95
	v_add_f32_e32 v96, 1.0, v96
	v_add_f32_e32 v97, 1.0, v97
	v_rcp_f32_e32 v94, v94
	v_rcp_f32_e32 v95, v95
	v_rcp_f32_e32 v96, v96
	v_rcp_f32_e32 v97, v97
	s_waitcnt vmcnt(12)
	v_lshlrev_b32_e32 v112, 16, v92
	v_and_b32_e32 v113, 0xffff0000, v92
	v_lshlrev_b32_e32 v90, 16, v91
	v_and_b32_e32 v91, 0xffff0000, v91
	v_lshlrev_b32_e32 v92, 16, v93
	v_and_b32_e32 v93, 0xffff0000, v93
	s_lshl_b32 s50, s18, 11
	s_or_b32 s18, s17, 3
	v_pk_fma_f32 v[94:95], v[94:95], v[110:111], v[112:113]
	v_pk_fma_f32 v[90:91], v[96:97], v[90:91], v[92:93]
	s_or_b32 s25, s18, s9
	v_cvt_pk_bf16_f32 v92, v94, v95
	v_cvt_pk_bf16_f32 v93, v90, v91
	v_lshl_add_u64 v[90:91], v[72:73], 0, s[50:51]
	s_mulk_i32 s25, 0x410
	global_store_dwordx2 v[90:91], v[92:93], off
	v_add_u32_e32 v90, s25, v109
	ds_read_b128 v[90:93], v90
	v_readlane_b32 s19, v107, s18
	v_readlane_b32 s24, v108, s18
	s_waitcnt vmcnt(12)
	v_lshlrev_b32_e32 v94, 16, v86
	v_and_b32_e32 v95, 0xffff0000, v86
	s_waitcnt lgkmcnt(0)
	v_fma_f32 v90, -v0, s19, v90
	v_fma_f32 v91, -v101, s19, v91
	v_fma_f32 v92, -v103, s19, v92
	v_fma_f32 v93, -v105, s19, v93
	v_fma_f32 v90, s24, v90, v100
	v_fma_f32 v91, s24, v91, v102
	v_fma_f32 v92, s24, v92, v104
	v_fma_f32 v93, s24, v93, v106
	v_mul_f32_e32 v90, 0xbfb8aa3b, v90
	v_mul_f32_e32 v91, 0xbfb8aa3b, v91
	v_mul_f32_e32 v92, 0xbfb8aa3b, v92
	v_mul_f32_e32 v93, 0xbfb8aa3b, v93
	v_exp_f32_e32 v90, v90
	v_exp_f32_e32 v91, v91
	v_exp_f32_e32 v92, v92
	v_exp_f32_e32 v93, v93
	v_add_f32_e32 v90, 1.0, v90
	v_add_f32_e32 v91, 1.0, v91
	v_add_f32_e32 v92, 1.0, v92
	v_add_f32_e32 v93, 1.0, v93
	v_rcp_f32_e32 v90, v90
	v_rcp_f32_e32 v91, v91
	v_rcp_f32_e32 v92, v92
	v_rcp_f32_e32 v93, v93
	s_waitcnt vmcnt(11)
	v_lshlrev_b32_e32 v96, 16, v88
	v_and_b32_e32 v97, 0xffff0000, v88
	v_lshlrev_b32_e32 v86, 16, v87
	v_and_b32_e32 v87, 0xffff0000, v87
	v_lshlrev_b32_e32 v88, 16, v89
	v_and_b32_e32 v89, 0xffff0000, v89
	s_lshl_b32 s50, s18, 11
	s_or_b32 s18, s17, 4
	v_pk_fma_f32 v[90:91], v[90:91], v[94:95], v[96:97]
	v_pk_fma_f32 v[86:87], v[92:93], v[86:87], v[88:89]
	s_or_b32 s25, s18, s9
	v_cvt_pk_bf16_f32 v88, v90, v91
	v_cvt_pk_bf16_f32 v89, v86, v87
	v_lshl_add_u64 v[86:87], v[72:73], 0, s[50:51]
	s_mulk_i32 s25, 0x410
	global_store_dwordx2 v[86:87], v[88:89], off
	v_add_u32_e32 v86, s25, v109
	ds_read_b128 v[86:89], v86
	v_readlane_b32 s19, v107, s18
	v_readlane_b32 s24, v108, s18
	s_waitcnt vmcnt(11)
	v_lshlrev_b32_e32 v90, 16, v82
	v_and_b32_e32 v91, 0xffff0000, v82
	s_waitcnt lgkmcnt(0)
; DI unsigned pack2(float a, float b) { fl2_t v = {a, b}; bf2_t r = __builtin_convertvector(v, bf2_t); return __builtin_bit_cast(unsigned, r); }
; DI float bflo(unsigned u) { return __uint_as_float(u << 16); }
; DI float bfhi(unsigned u) { return __uint_as_float(u & 0xffff0000u); }
; DI float sigmoidf_(float x) { return __builtin_amdgcn_rcpf(1.f + __builtin_amdgcn_exp2f(-1.4426950408889634f * x)); }
; DI float rl(float v, int srclane) { return __int_as_float(__builtin_amdgcn_readlane(__float_as_int(v), srclane)); }
; DI void epi_rows(const Params& p, int L, int ekind, const float* T, int rbase, int bcol) {
;     ...
;         for (int i = 0; i < 8; ++i) {
;           const int ri = ch * 8 + i;
;           const float mu = rl(rs_l.mu, ri), rstd = rl(rs_l.rstd, ri);
;           f32x4 t = *(const f32x4*)(T + (lr0 + ri) * TSTR + c4);
;           float sf[4] = {bflo(sv[i][0]), bfhi(sv[i][0]), bflo(sv[i][1]), bfhi(sv[i][1])};
;           float v[4];
;           for (int k = 0; k < 4; ++k) v[k] = sigmoidf_(rstd * (t[k] - mu * cs4[k]) + bw4[k]) * sf[k];
;           if (!a) { v[0] += bflo(mv[i][0]); v[1] += bfhi(mv[i][0]); v[2] += bflo(mv[i][1]); v[3] += bfhi(mv[i][1]); }
;           u32x2 o; o[0] = pack2(v[0], v[1]); o[1] = pack2(v[2], v[3]);
;           stg<u32x2>(Mx + (size_t)ri * 1024, o);
;         }
;       }
	v_fma_f32 v86, -v0, s19, v86
	v_fma_f32 v87, -v101, s19, v87
	v_fma_f32 v88, -v103, s19, v88
	v_fma_f32 v89, -v105, s19, v89
	v_fma_f32 v86, s24, v86, v100
	v_fma_f32 v87, s24, v87, v102
	v_fma_f32 v88, s24, v88, v104
	v_fma_f32 v89, s24, v89, v106
	v_mul_f32_e32 v86, 0xbfb8aa3b, v86
	v_mul_f32_e32 v87, 0xbfb8aa3b, v87
	v_mul_f32_e32 v88, 0xbfb8aa3b, v88
	v_mul_f32_e32 v89, 0xbfb8aa3b, v89
	v_exp_f32_e32 v86, v86
	v_exp_f32_e32 v87, v87
	v_exp_f32_e32 v88, v88
	v_exp_f32_e32 v89, v89
	v_add_f32_e32 v86, 1.0, v86
	v_add_f32_e32 v87, 1.0, v87
	v_add_f32_e32 v88, 1.0, v88
	v_add_f32_e32 v89, 1.0, v89
	v_rcp_f32_e32 v86, v86
	v_rcp_f32_e32 v87, v87
	v_rcp_f32_e32 v88, v88
	v_rcp_f32_e32 v89, v89
	s_waitcnt vmcnt(10)
	v_lshlrev_b32_e32 v92, 16, v84
	v_and_b32_e32 v93, 0xffff0000, v84
	v_lshlrev_b32_e32 v82, 16, v83
	v_and_b32_e32 v83, 0xffff0000, v83
	v_lshlrev_b32_e32 v84, 16, v85
	v_and_b32_e32 v85, 0xffff0000, v85
	s_lshl_b32 s50, s18, 11
	s_or_b32 s18, s17, 5
	v_pk_fma_f32 v[86:87], v[86:87], v[90:91], v[92:93]
	v_pk_fma_f32 v[82:83], v[88:89], v[82:83], v[84:85]
	s_or_b32 s25, s18, s9
	v_cvt_pk_bf16_f32 v84, v86, v87
	v_cvt_pk_bf16_f32 v85, v82, v83
	v_lshl_add_u64 v[82:83], v[72:73], 0, s[50:51]
	s_mulk_i32 s25, 0x410
	global_store_dwordx2 v[82:83], v[84:85], off
	v_add_u32_e32 v82, s25, v109
	ds_read_b128 v[82:85], v82
	v_readlane_b32 s19, v107, s18
	v_readlane_b32 s24, v108, s18
	s_waitcnt vmcnt(10)
	v_lshlrev_b32_e32 v86, 16, v78
	v_and_b32_e32 v87, 0xffff0000, v78
	s_waitcnt lgkmcnt(0)
	v_fma_f32 v82, -v0, s19, v82
	v_fma_f32 v83, -v101, s19, v83
	v_fma_f32 v84, -v103, s19, v84
	v_fma_f32 v85, -v105, s19, v85
	v_fma_f32 v82, s24, v82, v100
	v_fma_f32 v83, s24, v83, v102
	v_fma_f32 v84, s24, v84, v104
	v_fma_f32 v85, s24, v85, v106
	v_mul_f32_e32 v82, 0xbfb8aa3b, v82
	v_mul_f32_e32 v83, 0xbfb8aa3b, v83
	v_mul_f32_e32 v84, 0xbfb8aa3b, v84
	v_mul_f32_e32 v85, 0xbfb8aa3b, v85
	v_exp_f32_e32 v82, v82
	v_exp_f32_e32 v83, v83
	v_exp_f32_e32 v84, v84
	v_exp_f32_e32 v85, v85
	v_add_f32_e32 v82, 1.0, v82
	v_add_f32_e32 v83, 1.0, v83
	v_add_f32_e32 v84, 1.0, v84
	v_add_f32_e32 v85, 1.0, v85
	v_rcp_f32_e32 v82, v82
	v_rcp_f32_e32 v83, v83
	v_rcp_f32_e32 v84, v84
	v_rcp_f32_e32 v85, v85
	s_waitcnt vmcnt(9)
	v_lshlrev_b32_e32 v88, 16, v80
	v_and_b32_e32 v89, 0xffff0000, v80
	v_lshlrev_b32_e32 v78, 16, v79
	v_and_b32_e32 v79, 0xffff0000, v79
	v_lshlrev_b32_e32 v80, 16, v81
	v_and_b32_e32 v81, 0xffff0000, v81
	s_lshl_b32 s50, s18, 11
	s_or_b32 s18, s17, 6
	v_pk_fma_f32 v[82:83], v[82:83], v[86:87], v[88:89]
	v_pk_fma_f32 v[78:79], v[84:85], v[78:79], v[80:81]
	s_or_b32 s25, s18, s9
	v_cvt_pk_bf16_f32 v80, v82, v83
	v_cvt_pk_bf16_f32 v81, v78, v79
	v_lshl_add_u64 v[78:79], v[72:73], 0, s[50:51]
	s_mulk_i32 s25, 0x410
	global_store_dwordx2 v[78:79], v[80:81], off
	v_add_u32_e32 v78, s25, v109
	ds_read_b128 v[78:81], v78
	v_readlane_b32 s19, v107, s18
	v_readlane_b32 s24, v108, s18
	s_waitcnt vmcnt(9)
	v_lshlrev_b32_e32 v82, 16, v74
	v_and_b32_e32 v83, 0xffff0000, v74
	s_waitcnt lgkmcnt(0)
	v_fma_f32 v78, -v0, s19, v78
	v_fma_f32 v79, -v101, s19, v79
	v_fma_f32 v80, -v103, s19, v80
	v_fma_f32 v81, -v105, s19, v81
	v_fma_f32 v78, s24, v78, v100
	v_fma_f32 v79, s24, v79, v102
	v_fma_f32 v80, s24, v80, v104
	v_fma_f32 v81, s24, v81, v106
	v_mul_f32_e32 v78, 0xbfb8aa3b, v78
	v_mul_f32_e32 v79, 0xbfb8aa3b, v79
	v_mul_f32_e32 v80, 0xbfb8aa3b, v80
	v_mul_f32_e32 v81, 0xbfb8aa3b, v81
	v_exp_f32_e32 v78, v78
	v_exp_f32_e32 v79, v79
	v_exp_f32_e32 v80, v80
	v_exp_f32_e32 v81, v81
	v_add_f32_e32 v78, 1.0, v78
	v_add_f32_e32 v79, 1.0, v79
	v_add_f32_e32 v80, 1.0, v80
	v_add_f32_e32 v81, 1.0, v81
	v_rcp_f32_e32 v78, v78
	v_rcp_f32_e32 v79, v79
	v_rcp_f32_e32 v80, v80
	v_rcp_f32_e32 v81, v81
	s_waitcnt vmcnt(8)
	v_lshlrev_b32_e32 v84, 16, v76
	v_and_b32_e32 v85, 0xffff0000, v76
	v_lshlrev_b32_e32 v74, 16, v75
	v_and_b32_e32 v75, 0xffff0000, v75
	v_lshlrev_b32_e32 v76, 16, v77
	v_and_b32_e32 v77, 0xffff0000, v77
	s_or_b32 s17, s17, 7
	v_pk_fma_f32 v[78:79], v[78:79], v[82:83], v[84:85]
	v_pk_fma_f32 v[74:75], v[80:81], v[74:75], v[76:77]
	s_lshl_b32 s50, s18, 11
	s_or_b32 s24, s17, s9
	v_cvt_pk_bf16_f32 v76, v78, v79
	v_cvt_pk_bf16_f32 v77, v74, v75
	v_lshl_add_u64 v[74:75], v[72:73], 0, s[50:51]
	s_mulk_i32 s24, 0x410
	global_store_dwordx2 v[74:75], v[76:77], off
	v_add_u32_e32 v74, s24, v109
	ds_read_b128 v[74:77], v74
	v_readlane_b32 s18, v107, s17
	v_readlane_b32 s19, v108, s17
	s_waitcnt vmcnt(8)
	v_lshlrev_b32_e32 v78, 16, v66
	v_and_b32_e32 v79, 0xffff0000, v66
	s_waitcnt lgkmcnt(0)
	v_fma_f32 v74, -v0, s18, v74
	v_fma_f32 v75, -v101, s18, v75
	v_fma_f32 v76, -v103, s18, v76
	v_fma_f32 v77, -v105, s18, v77
	v_fma_f32 v74, s19, v74, v100
	v_fma_f32 v75, s19, v75, v102
	v_fma_f32 v76, s19, v76, v104
	v_fma_f32 v77, s19, v77, v106
	v_mul_f32_e32 v74, 0xbfb8aa3b, v74
	v_mul_f32_e32 v75, 0xbfb8aa3b, v75
	v_mul_f32_e32 v76, 0xbfb8aa3b, v76
	v_mul_f32_e32 v77, 0xbfb8aa3b, v77
	v_exp_f32_e32 v74, v74
	v_exp_f32_e32 v75, v75
	v_exp_f32_e32 v76, v76
	v_exp_f32_e32 v77, v77
	v_add_f32_e32 v74, 1.0, v74
	v_add_f32_e32 v75, 1.0, v75
	v_add_f32_e32 v76, 1.0, v76
	v_add_f32_e32 v77, 1.0, v77
	v_rcp_f32_e32 v74, v74
	v_rcp_f32_e32 v75, v75
	v_rcp_f32_e32 v76, v76
	v_rcp_f32_e32 v77, v77
	s_waitcnt vmcnt(7)
	v_lshlrev_b32_e32 v80, 16, v68
	v_and_b32_e32 v81, 0xffff0000, v68
	v_lshlrev_b32_e32 v66, 16, v67
	v_and_b32_e32 v67, 0xffff0000, v67
	v_lshlrev_b32_e32 v68, 16, v69
	v_and_b32_e32 v69, 0xffff0000, v69
	v_pk_fma_f32 v[74:75], v[74:75], v[78:79], v[80:81]
	v_pk_fma_f32 v[66:67], v[76:77], v[66:67], v[68:69]
	s_lshl_b32 s50, s17, 11
	v_cvt_pk_bf16_f32 v68, v74, v75
	v_cvt_pk_bf16_f32 v69, v66, v67
	v_lshl_add_u64 v[66:67], v[72:73], 0, s[50:51]
	global_store_dwordx2 v[66:67], v[68:69], off
	s_cbranch_vccnz .LBB0_1765
; DI void epi_dispatch(const Params& p, int L, int ekind, f32x4 (&acc)[2][2][4][2], int brow, int bcol, int, int, int, int) {
;     ...
;   for (int ai = 0; ai < 2; ++ai) {
;     __syncthreads();
;     #pragma unroll
;     for (int bj = 0; bj < 2; ++bj)
;       #pragma unroll
;       for (int m = 0; m < 4; ++m)
;         #pragma unroll
;         for (int n = 0; n < 2; ++n)
;           #pragma unroll
;           for (int j = 0; j < 4; ++j) tw[(m * 16 + j) * TSTR + bj * 128 + n * 16] = acc[ai][bj][m][n][j];
;     __syncthreads();
	v_readlane_b32 s16, v254, 25
	v_readlane_b32 s18, v254, 27
	v_readlane_b32 s19, v254, 28
	s_mov_b64 s[4:5], s[18:19]
	v_mov_b32_e32 v0, v178
	s_barrier
	ds_write2_b32 v130, v2, v18 offset1:16
	ds_write2_b32 v114, v3, v19 offset0:4 offset1:20
	ds_write2_b32 v115, v4, v20 offset0:8 offset1:24
	ds_write2_b32 v116, v5, v21 offset0:12 offset1:28
	ds_write2_b32 v117, v6, v22 offset0:64 offset1:80
	ds_write2_b32 v126, v7, v23 offset0:68 offset1:84
	ds_write2_b32 v127, v8, v24 offset0:72 offset1:88
	ds_write2_b32 v128, v9, v25 offset0:76 offset1:92
	ds_write2_b32 v136, v10, v26 offset0:128 offset1:144
	ds_write2_b32 v129, v11, v27 offset0:132 offset1:148
	ds_write2_b32 v131, v12, v28 offset0:136 offset1:152
	ds_write2_b32 v132, v13, v29 offset0:140 offset1:156
	ds_write2_b32 v137, v14, v30 offset0:192 offset1:208
	ds_write2_b32 v133, v15, v31 offset0:196 offset1:212
	ds_write2_b32 v134, v16, v32 offset0:200 offset1:216
	ds_write2_b32 v135, v17, v33 offset0:204 offset1:220
	ds_write2_b32 v130, v34, v50 offset0:128 offset1:144
	ds_write2_b32 v114, v35, v51 offset0:132 offset1:148
	ds_write2_b32 v115, v36, v52 offset0:136 offset1:152
	ds_write2_b32 v116, v37, v53 offset0:140 offset1:156
	ds_write2_b32 v117, v38, v54 offset0:192 offset1:208
	ds_write2_b32 v126, v39, v55 offset0:196 offset1:212
	ds_write2_b32 v127, v40, v56 offset0:200 offset1:216
	ds_write2_b32 v128, v41, v57 offset0:204 offset1:220
	ds_write2_b32 v129, v42, v58 offset1:16
	ds_write2_b32 v131, v43, v59 offset0:4 offset1:20
	ds_write2_b32 v132, v44, v60 offset0:8 offset1:24
	ds_write2_b32 v98, v45, v61 offset0:12 offset1:28
	ds_write2_b32 v133, v46, v62 offset0:64 offset1:80
	ds_write2_b32 v134, v47, v63 offset0:68 offset1:84
	ds_write2_b32 v135, v48, v64 offset0:72 offset1:88
	ds_write2_b32 v99, v49, v65 offset0:76 offset1:92
	s_waitcnt lgkmcnt(0)
	s_barrier
; DI float fxc(const i64* p) { return (float)(*p) * FXC_INV; }
; DI RowStat row_stat(const i64* st, int row) {
;   float s = (float)st[2 * (size_t)row] * FXS_INV, q = (float)st[2 * (size_t)row + 1] * FXS_INV;
;   float mu = s * (1.f / 1024.f);
;   float var = fmaxf(q * (1.f / 1024.f) - mu * mu, 0.f);
;   RowStat r; r.mu = mu; r.rstd = rsqrtf(var + 1e-5f); return r;
; DI void epi_rows(const Params& p, int L, int ekind, const float* T, int rbase, int bcol) {
;     ...
;       const i64* st = ST_(L, 0); const int co = a ? CS_WGA : CS_WGB;
;       const size_t off0 = (size_t)(rbase + lr0) * 1024 + bcol + c4;
;       const u16* src = (const u16*)(R + (a ? R_MX : R_GT)) + off0; u16* Mx = (u16*)(R + R_MX) + off0;
;       f32x4 cs4, bw4;
;       for (int k = 0; k < 4; ++k) { cs4[k] = fxc(cs + co + bcol + c4 + k); bw4[k] = fxc(bw + co + bcol + c4 + k); }
;       RowStat rs_l = row_stat(st, myrow);
	v_readlane_b32 s17, v254, 26
	s_add_u32 s16, s4, s12
	v_readfirstlane_b32 s9, v0
	s_addc_u32 s17, s5, s13
	s_ashr_i32 s9, s9, 2
	s_and_b32 s9, s9, -16
	v_lshlrev_b32_e32 v2, 2, v0
	s_add_i32 s12, s9, s8
	v_and_b32_e32 v12, 0xfc, v2
	s_ashr_i32 s13, s12, 31
	v_and_or_b32 v2, v0, 15, s12
	s_lshl_b64 s[12:13], s[12:13], 10
	v_or_b32_e32 v4, s6, v12
	v_mov_b32_e32 v5, s7
	v_lshl_add_u64 v[4:5], s[12:13], 0, v[4:5]
	v_lshl_add_u64 v[4:5], v[4:5], 1, s[4:5]
	s_mov_b64 s[6:7], 0xe1cda00
	v_lshl_add_u64 v[6:7], v[4:5], 0, s[6:7]
	s_add_u32 s6, s16, s10
	v_lshlrev_b32_e32 v0, 3, v12
	s_addc_u32 s7, s17, s11
	v_lshl_add_u64 v[18:19], s[6:7], 0, v[0:1]
	s_mov_b64 s[6:7], 0x39e800
	v_lshl_add_u64 v[10:11], v[18:19], 0, s[6:7]
	s_mov_b64 s[6:7], 0x3d9800
	v_lshl_add_u64 v[8:9], v[18:19], 0, s[6:7]
	s_mov_b32 s6, 0x39e000
	v_add_co_u32_e32 v14, vcc, s6, v18
	s_mov_b32 s7, 0x3d9000
	s_nop 0
	v_addc_co_u32_e32 v15, vcc, 0, v19, vcc
	flat_load_dwordx4 v[14:17], v[14:15] offset:2048
	s_add_u32 s4, s4, s14
	s_addc_u32 s5, s5, s15
	s_mov_b64 s[10:11], 0xa0cda00
	s_mov_b32 s6, 0
	v_lshl_add_u32 v43, v12, 2, 0
	v_add_co_u32_e32 v192, vcc, s7, v18
	s_nop 1
	v_addc_co_u32_e32 v193, vcc, 0, v19, vcc
	flat_load_dwordx4 v[188:191], v[192:193] offset:2048
	flat_load_dwordx4 v[196:199], v[10:11] offset:16
	flat_load_dwordx4 v[204:207], v[8:9] offset:16
	v_mov_b32_e32 v216, v2
	v_ashrrev_i32_e32 v217, 31, v216
	v_lshl_add_u64 v[216:217], v[216:217], 4, s[4:5]
	flat_load_dwordx4 v[212:215], v[216:217]
	s_waitcnt vmcnt(0) lgkmcnt(0)
	v_xor_b32_e32 v0, v14, v15
	v_ashrrev_i32_e32 v0, 31, v0
	v_ffbh_i32_e32 v3, v15
	v_add_u32_e32 v0, 32, v0
	v_add_u32_e32 v3, -1, v3
	v_min_u32_e32 v0, v3, v0
	v_lshlrev_b64 v[14:15], v0, v[14:15]
	v_min_u32_e32 v3, 1, v14
	v_add_co_u32_e32 v14, vcc, s7, v18
	v_or_b32_e32 v3, v15, v3
	s_nop 0
	v_addc_co_u32_e32 v15, vcc, 0, v19, vcc
	v_mov_b64_e32 v[18:19], v[188:189]
	v_mov_b64_e32 v[20:21], v[190:191]
	v_cvt_f32_i32_e32 v3, v3
	v_sub_u32_e32 v0, 32, v0
	v_ldexp_f32 v0, v3, v0
	v_mul_f32_e32 v0, 0x2f800000, v0
	s_waitcnt vmcnt(0) lgkmcnt(0)
	v_xor_b32_e32 v3, v18, v19
	v_ashrrev_i32_e32 v3, 31, v3
	v_ffbh_i32_e32 v13, v19
	v_add_u32_e32 v3, 32, v3
	v_add_u32_e32 v13, -1, v13
	v_min_u32_e32 v3, v13, v3
	v_lshlrev_b64 v[14:15], v3, v[18:19]
	v_min_u32_e32 v13, 1, v14
	v_or_b32_e32 v13, v15, v13
	v_cvt_f32_i32_e32 v13, v13
	v_sub_u32_e32 v3, 32, v3
	v_ldexp_f32 v3, v13, v3
	v_mul_f32_e32 v34, 0x2f800000, v3
	v_xor_b32_e32 v3, v16, v17
	v_ashrrev_i32_e32 v3, 31, v3
	v_ffbh_i32_e32 v13, v17
	v_add_u32_e32 v3, 32, v3
	v_add_u32_e32 v13, -1, v13
	v_min_u32_e32 v3, v13, v3
	v_lshlrev_b64 v[14:15], v3, v[16:17]
	v_min_u32_e32 v13, 1, v14
	v_or_b32_e32 v13, v15, v13
	v_cvt_f32_i32_e32 v13, v13
	v_sub_u32_e32 v3, 32, v3
	v_ldexp_f32 v3, v13, v3
	v_mul_f32_e32 v35, 0x2f800000, v3
	v_xor_b32_e32 v3, v20, v21
	v_ashrrev_i32_e32 v3, 31, v3
	v_ffbh_i32_e32 v13, v21
	v_add_u32_e32 v3, 32, v3
	v_add_u32_e32 v13, -1, v13
	v_min_u32_e32 v3, v13, v3
	v_lshlrev_b64 v[14:15], v3, v[20:21]
	v_min_u32_e32 v13, 1, v14
	v_or_b32_e32 v13, v15, v13
	v_mov_b64_e32 v[14:15], v[196:197]
	v_mov_b64_e32 v[16:17], v[198:199]
	v_cvt_f32_i32_e32 v13, v13
	v_sub_u32_e32 v3, 32, v3
	v_ldexp_f32 v3, v13, v3
	v_mul_f32_e32 v36, 0x2f800000, v3
	s_waitcnt vmcnt(0) lgkmcnt(0)
	v_xor_b32_e32 v3, v14, v15
	v_ashrrev_i32_e32 v3, 31, v3
	v_ffbh_i32_e32 v10, v15
	v_add_u32_e32 v3, 32, v3
	v_add_u32_e32 v10, -1, v10
	v_min_u32_e32 v3, v10, v3
	v_lshlrev_b64 v[10:11], v3, v[14:15]
	v_min_u32_e32 v10, 1, v10
	v_or_b32_e32 v10, v11, v10
	v_cvt_f32_i32_e32 v10, v10
	v_sub_u32_e32 v3, 32, v3
	v_ldexp_f32 v3, v10, v3
	v_mov_b64_e32 v[8:9], v[204:205]
	v_mov_b64_e32 v[10:11], v[206:207]
	v_mul_f32_e32 v37, 0x2f800000, v3
	s_waitcnt vmcnt(0) lgkmcnt(0)
	v_xor_b32_e32 v3, v8, v9
	v_ashrrev_i32_e32 v3, 31, v3
	v_ffbh_i32_e32 v13, v9
	v_add_u32_e32 v3, 32, v3
	v_add_u32_e32 v13, -1, v13
	v_min_u32_e32 v3, v13, v3
	v_lshlrev_b64 v[8:9], v3, v[8:9]
	v_min_u32_e32 v8, 1, v8
	v_or_b32_e32 v8, v9, v8
	v_cvt_f32_i32_e32 v8, v8
	v_sub_u32_e32 v3, 32, v3
	v_ldexp_f32 v3, v8, v3
	v_mul_f32_e32 v38, 0x2f800000, v3
	v_xor_b32_e32 v3, v16, v17
	v_ashrrev_i32_e32 v3, 31, v3
	v_ffbh_i32_e32 v8, v17
	v_add_u32_e32 v3, 32, v3
	v_add_u32_e32 v8, -1, v8
	v_min_u32_e32 v3, v8, v3
	v_lshlrev_b64 v[8:9], v3, v[16:17]
	v_min_u32_e32 v8, 1, v8
	v_or_b32_e32 v8, v9, v8
	v_cvt_f32_i32_e32 v8, v8
	v_sub_u32_e32 v3, 32, v3
	v_ldexp_f32 v3, v8, v3
	v_mul_f32_e32 v39, 0x2f800000, v3
	v_xor_b32_e32 v3, v10, v11
	v_ashrrev_i32_e32 v3, 31, v3
	v_ffbh_i32_e32 v8, v11
	v_add_u32_e32 v3, 32, v3
	v_add_u32_e32 v8, -1, v8
	v_min_u32_e32 v3, v8, v3
	v_lshlrev_b64 v[8:9], v3, v[10:11]
	v_min_u32_e32 v8, 1, v8
	v_or_b32_e32 v8, v9, v8
	v_cvt_f32_i32_e32 v8, v8
	v_sub_u32_e32 v3, 32, v3
	v_ldexp_f32 v3, v8, v3
	v_mul_f32_e32 v40, 0x2f800000, v3
	v_ashrrev_i32_e32 v3, 31, v2
	v_lshl_add_u64 v[2:3], v[2:3], 4, s[4:5]
	v_lshl_add_u64 v[8:9], v[4:5], 0, s[10:11]
	v_mov_b64_e32 v[2:3], v[212:213]
	v_mov_b64_e32 v[4:5], v[214:215]
	s_mov_b32 s4, 0x3a800000
	s_waitcnt vmcnt(0) lgkmcnt(0)
	v_xor_b32_e32 v10, v2, v3
	v_ashrrev_i32_e32 v10, 31, v10
	v_ffbh_i32_e32 v11, v3
	v_add_u32_e32 v10, 32, v10
	v_add_u32_e32 v11, -1, v11
	v_min_u32_e32 v10, v11, v10
	v_lshlrev_b64 v[2:3], v10, v[2:3]
	v_min_u32_e32 v2, 1, v2
	v_or_b32_e32 v2, v3, v2
	v_cvt_f32_i32_e32 v2, v2
	v_sub_u32_e32 v3, 32, v10
	v_ldexp_f32 v2, v2, v3
	v_mul_f32_e32 v10, 0x33800000, v2
	v_xor_b32_e32 v2, v4, v5
	v_ashrrev_i32_e32 v2, 31, v2
	v_ffbh_i32_e32 v3, v5
	v_add_u32_e32 v2, 32, v2
	v_add_u32_e32 v3, -1, v3
	v_min_u32_e32 v11, v3, v2
	v_lshlrev_b64 v[2:3], v11, v[4:5]
	v_min_u32_e32 v2, 1, v2
	v_or_b32_e32 v2, v3, v2
	v_cvt_f32_i32_e32 v2, v2
	v_sub_u32_e32 v3, 32, v11
	v_mul_f32_e32 v41, 0x3a800000, v10
	v_ldexp_f32 v2, v2, v3
	v_mul_f32_e32 v2, 0x33800000, v2
	v_mul_f32_e32 v3, v41, v41
	v_fma_f32 v2, v2, s4, -v3
	v_max_f32_e32 v2, 0, v2
	v_add_f32_e32 v2, 0x3727c5ac, v2
	s_mov_b32 s4, 0x800000
	v_cmp_gt_f32_e32 vcc, s4, v2
	v_mul_f32_e32 v3, 0x4b800000, v2
	s_mov_b64 s[4:5], -1
	v_cndmask_b32_e32 v2, v2, v3, vcc
	v_rsq_f32_e32 v2, v2
	s_nop 0
	v_mul_f32_e32 v3, 0x45800000, v2
	v_cndmask_b32_e32 v42, v2, v3, vcc
